# K-loop LDS-DMA loads use saddr+32-bit voffset form (drops 16 64-bit VALU address adds per iteration per wave and their VGPR WAR serialization), on top of MFMA reorder
# speedup vs baseline: 1.0158x; 1.0158x over previous
; #define PG8_STAGE(bufoff, gbase, voff) do { _Pragma("unroll") for (int _i = 0; _i < 2; ++_i) \
;         __builtin_amdgcn_global_load_lds((const unsigned*)((const char*)(gbase) + (voff)[_i]), (LAS unsigned*)(lds + (bufoff) + ldsw + _i * 8192), 16, 0, 0); } while (0)
; #define PG8_LDA(dst, b, h) do { _Pragma("unroll") for (int m = 0; m < 4; ++m) _Pragma("unroll") for (int k = 0; k < 2; ++k) dst[m][k] = *(const LAS bf16x8*)(lds + PG8_SA(b, h) + aoff + m * 2048 + k * 1024); } while (0)
; #define PG8_LDB(dst, b, h) do { _Pragma("unroll") for (int n = 0; n < 2; ++n) _Pragma("unroll") for (int k = 0; k < 2; ++k) dst[n][k] = *(const LAS bf16x8*)(lds + PG8_SB(b, h) + boff + n * 2048 + k * 1024); } while (0)
; template <bool ALIGN_EPI, class Epi, class Sched>
; __device__ __forceinline__ void gemm_phase(LAS unsigned char* lds, const int lda, const int ldb, const int K, const Sched& S, const Epi& E, const size_t kstepA = (size_t)(BK * 2), const size_t kstepB = (size_t)(BK * 2)) {
;     ...
;         for (int t = 0; t < nt; t += 2) {
;             const bool last = (t == nt - 2);
;             const char* a1 = cA + (size_t)(t + 1) * kstepA;
;             const char* a2 = last ? nA : cA + (size_t)(t + 2) * kstepA; const char* b2 = last ? nB : cB + (size_t)(t + 2) * kstep;
;             const char* a3 = a2 + kstepA; const char* b3 = b2 + kstep;
;             PG8_LDB(B0, 0, 0); PG8_LDB(B1, 0, 1); PG8_SCHED; PG8_LDA(At, 0, 0); PG8_STAGE(PG8_SA(1, 1), a1 + hstepA, voffA);
;             PG8_WAIT_V(8); PG8_WAIT_L(0); PG8_BAR; PG8_MMA(0, 0, At, B0); PG8_MMA(0, 1, At, B1); PG8_BAR; PG8_SCHED;
;             PG8_LDA(At, 0, 1); PG8_STAGE(PG8_SB(0, 0), b2, voffB); PG8_STAGE(PG8_SB(0, 1), b2 + hstepB, voffB); PG8_STAGE(PG8_SA(0, 0), a2, voffA);
;             PG8_WAIT_V(8); PG8_WAIT_L(0); PG8_BAR; PG8_MMA(1, 0, At, B0); PG8_MMA(1, 1, At, B1); PG8_BAR; PG8_SCHED;
;             PG8_LDB(B0, 1, 0); PG8_LDB(B1, 1, 1); PG8_SCHED; PG8_LDA(At, 1, 0); PG8_STAGE(PG8_SA(0, 1), a2 + hstepA, voffA);
;             PG8_WAIT_V(8); PG8_WAIT_L(0); PG8_BAR; PG8_MMA(0, 0, At, B0); PG8_MMA(0, 1, At, B1); PG8_BAR; PG8_SCHED;
;             PG8_LDA(At, 1, 1); PG8_STAGE(PG8_SB(1, 0), b3, voffB); PG8_STAGE(PG8_SB(1, 1), b3 + hstepB, voffB); PG8_STAGE(PG8_SA(1, 0), a3, voffA);
;             PG8_WAIT_V(8); PG8_WAIT_L(0); PG8_BAR; PG8_MMA(1, 0, At, B0); PG8_MMA(1, 1, At, B1); PG8_BAR; PG8_SCHED;
.LBB0_139:
	ds_read_b128 v[154:157], v150
	ds_read_b128 v[158:161], v150 offset:1024
	ds_read_b128 v[162:165], v150 offset:2048
	ds_read_b128 v[166:169], v150 offset:3072
	ds_read_b128 v[170:173], v151
	ds_read_b128 v[174:177], v151 offset:1024
	ds_read_b128 v[178:181], v151 offset:2048
	ds_read_b128 v[194:197], v151 offset:3072
	s_add_u32 s54, s70, 0x1fc000
	s_addc_u32 s55, s71, 0
	s_cmp_eq_u32 s51, 28
	s_cselect_b32 s78, s6, s54
	s_cselect_b32 s79, s7, s55
	s_cselect_b32 s76, s68, s41
	s_cselect_b32 s77, s69, s49
	s_add_u32 s74, s78, 0x200000
	s_addc_u32 s75, s79, 0
	s_add_i32 m0, s20, 0xc000
	ds_read_b128 v[198:201], v152
	ds_read_b128 v[202:205], v152 offset:1024
	ds_read_b128 v[206:209], v152 offset:2048
	ds_read_b128 v[210:213], v152 offset:3072
	ds_read_b128 v[214:217], v152 offset:4096
	ds_read_b128 v[218:221], v152 offset:5120
	ds_read_b128 v[222:225], v152 offset:6144
	ds_read_b128 v[226:229], v152 offset:7168
	global_load_lds_dwordx4 v138, s[70:71]
	s_add_i32 m0, s20, 0xe000
	s_nop 0
	global_load_lds_dwordx4 v140, s[70:71]
	s_waitcnt vmcnt(8)
	s_waitcnt lgkmcnt(0)
	s_barrier
	s_setprio 1
	s_waitcnt lgkmcnt(0)
	v_mfma_f32_16x16x32_bf16 v[124:127], v[154:157], v[198:201], v[124:127]
	v_mfma_f32_16x16x32_bf16 v[124:127], v[158:161], v[202:205], v[124:127]
	v_mfma_f32_16x16x32_bf16 v[116:119], v[162:165], v[198:201], v[116:119]
	v_mfma_f32_16x16x32_bf16 v[116:119], v[166:169], v[202:205], v[116:119]
	v_mfma_f32_16x16x32_bf16 v[108:111], v[154:157], v[206:209], v[108:111]
	v_mfma_f32_16x16x32_bf16 v[108:111], v[158:161], v[210:213], v[108:111]
	v_mfma_f32_16x16x32_bf16 v[100:103], v[162:165], v[206:209], v[100:103]
	v_mfma_f32_16x16x32_bf16 v[100:103], v[166:169], v[210:213], v[100:103]
	v_mfma_f32_16x16x32_bf16 v[92:95], v[154:157], v[214:217], v[92:95]
	v_mfma_f32_16x16x32_bf16 v[92:95], v[158:161], v[218:221], v[92:95]
	v_mfma_f32_16x16x32_bf16 v[84:87], v[162:165], v[214:217], v[84:87]
	v_mfma_f32_16x16x32_bf16 v[84:87], v[166:169], v[218:221], v[84:87]
	v_mfma_f32_16x16x32_bf16 v[76:79], v[154:157], v[222:225], v[76:79]
	v_mfma_f32_16x16x32_bf16 v[76:79], v[158:161], v[226:229], v[76:79]
	v_mfma_f32_16x16x32_bf16 v[68:71], v[162:165], v[222:225], v[68:71]
	v_mfma_f32_16x16x32_bf16 v[68:71], v[166:169], v[226:229], v[68:71]
	s_setprio 0
	s_setprio 1
	v_mfma_f32_16x16x32_bf16 v[120:123], v[170:173], v[198:201], v[120:123]
	v_mfma_f32_16x16x32_bf16 v[120:123], v[174:177], v[202:205], v[120:123]
	v_mfma_f32_16x16x32_bf16 v[112:115], v[178:181], v[198:201], v[112:115]
	v_mfma_f32_16x16x32_bf16 v[112:115], v[194:197], v[202:205], v[112:115]
	v_mfma_f32_16x16x32_bf16 v[104:107], v[170:173], v[206:209], v[104:107]
	v_mfma_f32_16x16x32_bf16 v[104:107], v[174:177], v[210:213], v[104:107]
	v_mfma_f32_16x16x32_bf16 v[96:99], v[178:181], v[206:209], v[96:99]
	v_mfma_f32_16x16x32_bf16 v[96:99], v[194:197], v[210:213], v[96:99]
	v_mfma_f32_16x16x32_bf16 v[88:91], v[170:173], v[214:217], v[88:91]
	v_mfma_f32_16x16x32_bf16 v[88:91], v[174:177], v[218:221], v[88:91]
	v_mfma_f32_16x16x32_bf16 v[80:83], v[178:181], v[214:217], v[80:83]
	v_mfma_f32_16x16x32_bf16 v[80:83], v[194:197], v[218:221], v[80:83]
	v_mfma_f32_16x16x32_bf16 v[72:75], v[170:173], v[222:225], v[72:75]
	v_mfma_f32_16x16x32_bf16 v[72:75], v[174:177], v[226:229], v[72:75]
	v_mfma_f32_16x16x32_bf16 v[64:67], v[178:181], v[222:225], v[64:67]
	v_mfma_f32_16x16x32_bf16 v[64:67], v[194:197], v[226:229], v[64:67]
	s_setprio 0
	s_barrier
	s_add_i32 s54, s42, s18
	s_mov_b32 m0, s54
	ds_read_b128 v[198:201], v152 offset:16384
	ds_read_b128 v[202:205], v152 offset:17408
	ds_read_b128 v[206:209], v152 offset:18432
	ds_read_b128 v[210:213], v152 offset:19456
	ds_read_b128 v[214:217], v152 offset:20480
	ds_read_b128 v[218:221], v152 offset:21504
	ds_read_b128 v[222:225], v152 offset:22528
	ds_read_b128 v[226:229], v152 offset:23552
	global_load_lds_dwordx4 v132, s[76:77]
	s_add_i32 m0, s54, 0x2000
	s_add_u32 s54, s76, 0x4000
	s_addc_u32 s55, s77, 0
	s_add_i32 s56, s43, s18
	global_load_lds_dwordx4 v128, s[76:77]
	s_mov_b32 m0, s56
	s_nop 0
	global_load_lds_dwordx4 v132, s[54:55]
	s_add_i32 m0, s56, 0x2000
	s_nop 0
	global_load_lds_dwordx4 v128, s[54:55]
	s_mov_b32 m0, s20
	s_nop 0
	global_load_lds_dwordx4 v134, s[78:79]
	s_mov_b32 m0, s21
	s_nop 0
	global_load_lds_dwordx4 v130, s[78:79]
	s_waitcnt vmcnt(8)
	s_waitcnt lgkmcnt(0)
	s_barrier
	s_setprio 1
	s_waitcnt lgkmcnt(0)
	v_mfma_f32_16x16x32_bf16 v[60:63], v[154:157], v[198:201], v[60:63]
	v_mfma_f32_16x16x32_bf16 v[60:63], v[158:161], v[202:205], v[60:63]
	v_mfma_f32_16x16x32_bf16 v[52:55], v[162:165], v[198:201], v[52:55]
	v_mfma_f32_16x16x32_bf16 v[52:55], v[166:169], v[202:205], v[52:55]
	v_mfma_f32_16x16x32_bf16 v[44:47], v[154:157], v[206:209], v[44:47]
	v_mfma_f32_16x16x32_bf16 v[44:47], v[158:161], v[210:213], v[44:47]
	v_mfma_f32_16x16x32_bf16 v[36:39], v[162:165], v[206:209], v[36:39]
	v_mfma_f32_16x16x32_bf16 v[36:39], v[166:169], v[210:213], v[36:39]
	v_mfma_f32_16x16x32_bf16 v[28:31], v[154:157], v[214:217], v[28:31]
	v_mfma_f32_16x16x32_bf16 v[28:31], v[158:161], v[218:221], v[28:31]
	v_mfma_f32_16x16x32_bf16 v[20:23], v[162:165], v[214:217], v[20:23]
	v_mfma_f32_16x16x32_bf16 v[20:23], v[166:169], v[218:221], v[20:23]
	v_mfma_f32_16x16x32_bf16 v[12:15], v[154:157], v[222:225], v[12:15]
	v_mfma_f32_16x16x32_bf16 v[12:15], v[158:161], v[226:229], v[12:15]
	v_mfma_f32_16x16x32_bf16 v[4:7], v[162:165], v[222:225], v[4:7]
	v_mfma_f32_16x16x32_bf16 v[4:7], v[166:169], v[226:229], v[4:7]
	s_setprio 0
	s_setprio 1
	v_mfma_f32_16x16x32_bf16 v[56:59], v[170:173], v[198:201], v[56:59]
	v_mfma_f32_16x16x32_bf16 v[56:59], v[174:177], v[202:205], v[56:59]
	v_mfma_f32_16x16x32_bf16 v[48:51], v[178:181], v[198:201], v[48:51]
	v_mfma_f32_16x16x32_bf16 v[48:51], v[194:197], v[202:205], v[48:51]
	v_mfma_f32_16x16x32_bf16 v[40:43], v[170:173], v[206:209], v[40:43]
	v_mfma_f32_16x16x32_bf16 v[40:43], v[174:177], v[210:213], v[40:43]
	v_mfma_f32_16x16x32_bf16 v[32:35], v[178:181], v[206:209], v[32:35]
	v_mfma_f32_16x16x32_bf16 v[32:35], v[194:197], v[210:213], v[32:35]
	v_mfma_f32_16x16x32_bf16 v[24:27], v[170:173], v[214:217], v[24:27]
	v_mfma_f32_16x16x32_bf16 v[24:27], v[174:177], v[218:221], v[24:27]
	v_mfma_f32_16x16x32_bf16 v[16:19], v[178:181], v[214:217], v[16:19]
	v_mfma_f32_16x16x32_bf16 v[16:19], v[194:197], v[218:221], v[16:19]
	v_mfma_f32_16x16x32_bf16 v[8:11], v[170:173], v[222:225], v[8:11]
	v_mfma_f32_16x16x32_bf16 v[8:11], v[174:177], v[226:229], v[8:11]
	v_mfma_f32_16x16x32_bf16 v[0:3], v[178:181], v[222:225], v[0:3]
	v_mfma_f32_16x16x32_bf16 v[0:3], v[194:197], v[226:229], v[0:3]
	s_setprio 0
	s_barrier
; #define PG8_STAGE(bufoff, gbase, voff) do { _Pragma("unroll") for (int _i = 0; _i < 2; ++_i) \
;         __builtin_amdgcn_global_load_lds((const unsigned*)((const char*)(gbase) + (voff)[_i]), (LAS unsigned*)(lds + (bufoff) + ldsw + _i * 8192), 16, 0, 0); } while (0)
; #define PG8_LDA(dst, b, h) do { _Pragma("unroll") for (int m = 0; m < 4; ++m) _Pragma("unroll") for (int k = 0; k < 2; ++k) dst[m][k] = *(const LAS bf16x8*)(lds + PG8_SA(b, h) + aoff + m * 2048 + k * 1024); } while (0)
; #define PG8_LDB(dst, b, h) do { _Pragma("unroll") for (int n = 0; n < 2; ++n) _Pragma("unroll") for (int k = 0; k < 2; ++k) dst[n][k] = *(const LAS bf16x8*)(lds + PG8_SB(b, h) + boff + n * 2048 + k * 1024); } while (0)
; #define PG8_MMA(ai, bj, At, Bt) do { __builtin_amdgcn_s_setprio(1); _Pragma("unroll") for (int m = 0; m < 4; ++m) _Pragma("unroll") for (int n = 0; n < 2; ++n) _Pragma("unroll") for (int k = 0; k < 2; ++k) \
;         acc[ai][bj][m][n] = __builtin_amdgcn_mfma_f32_16x16x32_bf16(Bt[n][k], At[m][k], acc[ai][bj][m][n], 0, 0, 0); __builtin_amdgcn_s_setprio(0); } while (0)
; #define PG8_WAIT_V(n) asm volatile("s_waitcnt vmcnt(" #n ")" ::: "memory")
; #define PG8_WAIT_L(n) asm volatile("s_waitcnt lgkmcnt(" #n ")" ::: "memory")
; #define PG8_BAR __builtin_amdgcn_s_barrier()
; template <bool ALIGN_EPI, class Epi, class Sched>
; __device__ __forceinline__ void gemm_phase(LAS unsigned char* lds, const int lda, const int ldb, const int K, const Sched& S, const Epi& E, const size_t kstepA = (size_t)(BK * 2), const size_t kstepB = (size_t)(BK * 2)) {
;     ...
;             PG8_LDA(At, 0, 1); PG8_STAGE(PG8_SB(0, 0), b2, voffB); PG8_STAGE(PG8_SB(0, 1), b2 + hstepB, voffB); PG8_STAGE(PG8_SA(0, 0), a2, voffA);
;             PG8_WAIT_V(8); PG8_WAIT_L(0); PG8_BAR; PG8_MMA(1, 0, At, B0); PG8_MMA(1, 1, At, B1); PG8_BAR; PG8_SCHED;
;             PG8_LDB(B0, 1, 0); PG8_LDB(B1, 1, 1); PG8_SCHED; PG8_LDA(At, 1, 0); PG8_STAGE(PG8_SA(0, 1), a2 + hstepA, voffA);
;             PG8_WAIT_V(8); PG8_WAIT_L(0); PG8_BAR; PG8_MMA(0, 0, At, B0); PG8_MMA(0, 1, At, B1); PG8_BAR; PG8_SCHED;
;             PG8_LDA(At, 1, 1); PG8_STAGE(PG8_SB(1, 0), b3, voffB); PG8_STAGE(PG8_SB(1, 1), b3 + hstepB, voffB); PG8_STAGE(PG8_SA(1, 0), a3, voffA);
;             PG8_WAIT_V(8); PG8_WAIT_L(0); PG8_BAR; PG8_MMA(1, 0, At, B0); PG8_MMA(1, 1, At, B1); PG8_BAR; PG8_SCHED;
;         }
	s_add_i32 s56, 0, 0x18000
	v_add_u32_e32 v146, s56, v149
	s_add_i32 s57, 0, 0x1c000
	ds_read_b128 v[154:157], v146
	ds_read_b128 v[158:161], v146 offset:1024
	ds_read_b128 v[162:165], v146 offset:2048
	ds_read_b128 v[166:169], v146 offset:3072
	v_add_u32_e32 v146, s57, v149
	ds_read_b128 v[170:173], v146
	ds_read_b128 v[174:177], v146 offset:1024
	ds_read_b128 v[178:181], v146 offset:2048
	ds_read_b128 v[194:197], v146 offset:3072
	s_add_u32 s54, s78, 0x4000
	s_addc_u32 s55, s79, 0
	s_mov_b32 m0, s22
	ds_read_b128 v[198:201], v152 offset:32768
	ds_read_b128 v[202:205], v152 offset:33792
	ds_read_b128 v[206:209], v152 offset:34816
	ds_read_b128 v[210:213], v152 offset:35840
	ds_read_b128 v[214:217], v152 offset:36864
	ds_read_b128 v[218:221], v152 offset:37888
	ds_read_b128 v[222:225], v152 offset:38912
	ds_read_b128 v[226:229], v152 offset:39936
	global_load_lds_dwordx4 v134, s[54:55]
	s_mov_b32 m0, s23
	s_nop 0
	global_load_lds_dwordx4 v130, s[54:55]
	s_waitcnt vmcnt(8)
	s_waitcnt lgkmcnt(0)
	s_barrier
	s_setprio 1
	s_waitcnt lgkmcnt(0)
	v_mfma_f32_16x16x32_bf16 v[124:127], v[154:157], v[198:201], v[124:127]
	v_mfma_f32_16x16x32_bf16 v[124:127], v[158:161], v[202:205], v[124:127]
	v_mfma_f32_16x16x32_bf16 v[116:119], v[162:165], v[198:201], v[116:119]
	v_mfma_f32_16x16x32_bf16 v[116:119], v[166:169], v[202:205], v[116:119]
	v_mfma_f32_16x16x32_bf16 v[108:111], v[154:157], v[206:209], v[108:111]
	v_mfma_f32_16x16x32_bf16 v[108:111], v[158:161], v[210:213], v[108:111]
	v_mfma_f32_16x16x32_bf16 v[100:103], v[162:165], v[206:209], v[100:103]
	v_mfma_f32_16x16x32_bf16 v[100:103], v[166:169], v[210:213], v[100:103]
	v_mfma_f32_16x16x32_bf16 v[92:95], v[154:157], v[214:217], v[92:95]
	v_mfma_f32_16x16x32_bf16 v[92:95], v[158:161], v[218:221], v[92:95]
	v_mfma_f32_16x16x32_bf16 v[84:87], v[162:165], v[214:217], v[84:87]
	v_mfma_f32_16x16x32_bf16 v[84:87], v[166:169], v[218:221], v[84:87]
	v_mfma_f32_16x16x32_bf16 v[76:79], v[154:157], v[222:225], v[76:79]
	v_mfma_f32_16x16x32_bf16 v[76:79], v[158:161], v[226:229], v[76:79]
	v_mfma_f32_16x16x32_bf16 v[68:71], v[162:165], v[222:225], v[68:71]
	v_mfma_f32_16x16x32_bf16 v[68:71], v[166:169], v[226:229], v[68:71]
	s_setprio 0
	s_setprio 1
	v_mfma_f32_16x16x32_bf16 v[120:123], v[170:173], v[198:201], v[120:123]
	v_mfma_f32_16x16x32_bf16 v[120:123], v[174:177], v[202:205], v[120:123]
	v_mfma_f32_16x16x32_bf16 v[112:115], v[178:181], v[198:201], v[112:115]
	v_mfma_f32_16x16x32_bf16 v[112:115], v[194:197], v[202:205], v[112:115]
	v_mfma_f32_16x16x32_bf16 v[104:107], v[170:173], v[206:209], v[104:107]
	v_mfma_f32_16x16x32_bf16 v[104:107], v[174:177], v[210:213], v[104:107]
	v_mfma_f32_16x16x32_bf16 v[96:99], v[178:181], v[206:209], v[96:99]
	v_mfma_f32_16x16x32_bf16 v[96:99], v[194:197], v[210:213], v[96:99]
	v_mfma_f32_16x16x32_bf16 v[88:91], v[170:173], v[214:217], v[88:91]
	v_mfma_f32_16x16x32_bf16 v[88:91], v[174:177], v[218:221], v[88:91]
	v_mfma_f32_16x16x32_bf16 v[80:83], v[178:181], v[214:217], v[80:83]
	v_mfma_f32_16x16x32_bf16 v[80:83], v[194:197], v[218:221], v[80:83]
	v_mfma_f32_16x16x32_bf16 v[72:75], v[170:173], v[222:225], v[72:75]
	v_mfma_f32_16x16x32_bf16 v[72:75], v[174:177], v[226:229], v[72:75]
	v_mfma_f32_16x16x32_bf16 v[64:67], v[178:181], v[222:225], v[64:67]
	v_mfma_f32_16x16x32_bf16 v[64:67], v[194:197], v[226:229], v[64:67]
	s_setprio 0
	s_barrier
	s_add_u32 s54, s76, 0x160000
	s_addc_u32 s55, s77, 0
	s_add_i32 s56, s56, s18
	s_mov_b32 m0, s56
	ds_read_b128 v[198:201], v152 offset:49152
	ds_read_b128 v[202:205], v152 offset:50176
	ds_read_b128 v[206:209], v152 offset:51200
	ds_read_b128 v[210:213], v152 offset:52224
	ds_read_b128 v[214:217], v152 offset:53248
	ds_read_b128 v[218:221], v152 offset:54272
	ds_read_b128 v[222:225], v152 offset:55296
	ds_read_b128 v[226:229], v152 offset:56320
	global_load_lds_dwordx4 v132, s[54:55]
	s_add_i32 m0, s56, 0x2000
	s_nop 0
	global_load_lds_dwordx4 v128, s[54:55]
	s_add_u32 s54, s76, 0x164000
	s_addc_u32 s55, s77, 0
	s_add_i32 s56, s57, s18
	s_mov_b32 m0, s56
	s_nop 0
	global_load_lds_dwordx4 v132, s[54:55]
	s_add_i32 m0, s56, 0x2000
	s_nop 0
	global_load_lds_dwordx4 v128, s[54:55]
	s_mov_b32 m0, s31
	s_nop 0
	global_load_lds_dwordx4 v134, s[74:75]
	s_mov_b32 m0, s33
	s_nop 0
	global_load_lds_dwordx4 v130, s[74:75]
	s_waitcnt vmcnt(8)
	s_waitcnt lgkmcnt(0)
	s_barrier
	s_setprio 1
	s_waitcnt lgkmcnt(0)
	v_mfma_f32_16x16x32_bf16 v[60:63], v[154:157], v[198:201], v[60:63]
	v_mfma_f32_16x16x32_bf16 v[60:63], v[158:161], v[202:205], v[60:63]
	v_mfma_f32_16x16x32_bf16 v[52:55], v[162:165], v[198:201], v[52:55]
	v_mfma_f32_16x16x32_bf16 v[52:55], v[166:169], v[202:205], v[52:55]
	v_mfma_f32_16x16x32_bf16 v[44:47], v[154:157], v[206:209], v[44:47]
	v_mfma_f32_16x16x32_bf16 v[44:47], v[158:161], v[210:213], v[44:47]
	v_mfma_f32_16x16x32_bf16 v[36:39], v[162:165], v[206:209], v[36:39]
	v_mfma_f32_16x16x32_bf16 v[36:39], v[166:169], v[210:213], v[36:39]
	v_mfma_f32_16x16x32_bf16 v[28:31], v[154:157], v[214:217], v[28:31]
	v_mfma_f32_16x16x32_bf16 v[28:31], v[158:161], v[218:221], v[28:31]
	v_mfma_f32_16x16x32_bf16 v[20:23], v[162:165], v[214:217], v[20:23]
	v_mfma_f32_16x16x32_bf16 v[20:23], v[166:169], v[218:221], v[20:23]
	v_mfma_f32_16x16x32_bf16 v[12:15], v[154:157], v[222:225], v[12:15]
	v_mfma_f32_16x16x32_bf16 v[12:15], v[158:161], v[226:229], v[12:15]
	v_mfma_f32_16x16x32_bf16 v[4:7], v[162:165], v[222:225], v[4:7]
	v_mfma_f32_16x16x32_bf16 v[4:7], v[166:169], v[226:229], v[4:7]
	s_setprio 0
	s_setprio 1
	v_mfma_f32_16x16x32_bf16 v[56:59], v[170:173], v[198:201], v[56:59]
	v_mfma_f32_16x16x32_bf16 v[56:59], v[174:177], v[202:205], v[56:59]
	v_mfma_f32_16x16x32_bf16 v[48:51], v[178:181], v[198:201], v[48:51]
	v_mfma_f32_16x16x32_bf16 v[48:51], v[194:197], v[202:205], v[48:51]
	v_mfma_f32_16x16x32_bf16 v[40:43], v[170:173], v[206:209], v[40:43]
	v_mfma_f32_16x16x32_bf16 v[40:43], v[174:177], v[210:213], v[40:43]
	v_mfma_f32_16x16x32_bf16 v[32:35], v[178:181], v[206:209], v[32:35]
	v_mfma_f32_16x16x32_bf16 v[32:35], v[194:197], v[210:213], v[32:35]
	v_mfma_f32_16x16x32_bf16 v[24:27], v[170:173], v[214:217], v[24:27]
	v_mfma_f32_16x16x32_bf16 v[24:27], v[174:177], v[218:221], v[24:27]
	v_mfma_f32_16x16x32_bf16 v[16:19], v[178:181], v[214:217], v[16:19]
	v_mfma_f32_16x16x32_bf16 v[16:19], v[194:197], v[218:221], v[16:19]
	v_mfma_f32_16x16x32_bf16 v[8:11], v[170:173], v[222:225], v[8:11]
	v_mfma_f32_16x16x32_bf16 v[8:11], v[174:177], v[226:229], v[8:11]
	v_mfma_f32_16x16x32_bf16 v[0:3], v[178:181], v[222:225], v[0:3]
	v_mfma_f32_16x16x32_bf16 v[0:3], v[194:197], v[226:229], v[0:3]
	s_setprio 0
	s_barrier
	s_add_i32 s51, s51, 2
	s_add_u32 s41, s41, 0x2c0000
	s_addc_u32 s49, s49, 0
	s_add_u32 s70, s70, 0x400000
	s_addc_u32 s71, s71, 0
	s_cmp_gt_u32 s51, 29
	s_cbranch_scc0 .LBB0_139
	s_and_b64 vcc, exec, s[12:13]
	s_cbranch_vccz .LBB0_142
	s_barrier

; #define PG8_STAGE(bufoff, gbase, voff) do { _Pragma("unroll") for (int _i = 0; _i < 2; ++_i) \
;         __builtin_amdgcn_global_load_lds((const unsigned*)((const char*)(gbase) + (voff)[_i]), (LAS unsigned*)(lds + (bufoff) + ldsw + _i * 8192), 16, 0, 0); } while (0)
; #define PG8_LDA(dst, b, h) do { _Pragma("unroll") for (int m = 0; m < 4; ++m) _Pragma("unroll") for (int k = 0; k < 2; ++k) dst[m][k] = *(const LAS bf16x8*)(lds + PG8_SA(b, h) + aoff + m * 2048 + k * 1024); } while (0)
; #define PG8_LDB(dst, b, h) do { _Pragma("unroll") for (int n = 0; n < 2; ++n) _Pragma("unroll") for (int k = 0; k < 2; ++k) dst[n][k] = *(const LAS bf16x8*)(lds + PG8_SB(b, h) + boff + n * 2048 + k * 1024); } while (0)
; #define PG8_MMA(ai, bj, At, Bt) do { __builtin_amdgcn_s_setprio(1); _Pragma("unroll") for (int m = 0; m < 4; ++m) _Pragma("unroll") for (int n = 0; n < 2; ++n) _Pragma("unroll") for (int k = 0; k < 2; ++k) \
;         acc[ai][bj][m][n] = __builtin_amdgcn_mfma_f32_16x16x32_bf16(Bt[n][k], At[m][k], acc[ai][bj][m][n], 0, 0, 0); __builtin_amdgcn_s_setprio(0); } while (0)
; #define PG8_WAIT_V(n) asm volatile("s_waitcnt vmcnt(" #n ")" ::: "memory")
; #define PG8_WAIT_L(n) asm volatile("s_waitcnt lgkmcnt(" #n ")" ::: "memory")
; template <bool ALIGN_EPI, class Epi, class Sched>
; __device__ __forceinline__ void gemm_phase(LAS unsigned char* lds, const int lda, const int ldb, const int K, const Sched& S, const Epi& E, const size_t kstepA = (size_t)(BK * 2), const size_t kstepB = (size_t)(BK * 2)) {
;     ...
;         for (int t = 0; t < nt; t += 2) {
;             const bool last = (t == nt - 2);
;             const char* a1 = cA + (size_t)(t + 1) * kstepA;
;             const char* a2 = last ? nA : cA + (size_t)(t + 2) * kstepA; const char* b2 = last ? nB : cB + (size_t)(t + 2) * kstep;
;             const char* a3 = a2 + kstepA; const char* b3 = b2 + kstep;
;             PG8_LDB(B0, 0, 0); PG8_LDB(B1, 0, 1); PG8_SCHED; PG8_LDA(At, 0, 0); PG8_STAGE(PG8_SA(1, 1), a1 + hstepA, voffA);
;             PG8_WAIT_V(8); PG8_WAIT_L(0); PG8_BAR; PG8_MMA(0, 0, At, B0); PG8_MMA(0, 1, At, B1); PG8_BAR; PG8_SCHED;
;             PG8_LDA(At, 0, 1); PG8_STAGE(PG8_SB(0, 0), b2, voffB); PG8_STAGE(PG8_SB(0, 1), b2 + hstepB, voffB); PG8_STAGE(PG8_SA(0, 0), a2, voffA);
;             PG8_WAIT_V(8); PG8_WAIT_L(0); PG8_BAR; PG8_MMA(1, 0, At, B0); PG8_MMA(1, 1, At, B1); PG8_BAR; PG8_SCHED;
.LBB0_218:
	ds_read_b128 v[64:67], v193
	ds_read_b128 v[68:71], v193 offset:1024
	ds_read_b128 v[80:83], v193 offset:2048
	ds_read_b128 v[84:87], v193 offset:3072
	ds_read_b128 v[144:147], v232
	ds_read_b128 v[148:151], v232 offset:1024
	ds_read_b128 v[152:155], v232 offset:2048
	ds_read_b128 v[156:159], v232 offset:3072
	s_add_u32 s54, s82, 0x1fc000
	s_addc_u32 s55, s83, 0
	s_cmpk_eq_i32 s51, 0x54
	s_cselect_b32 vcc_lo, s6, s54
	s_cselect_b32 vcc_hi, s7, s55
	s_cselect_b32 s96, s78, s13
	s_cselect_b32 s97, s79, s50
	s_add_u32 s94, vcc_lo, 0x200000
	s_addc_u32 s95, vcc_hi, 0
	s_add_i32 m0, s19, 0xc000
	ds_read_b128 v[160:163], v233
	ds_read_b128 v[164:167], v233 offset:1024
	ds_read_b128 v[168:171], v233 offset:2048
	ds_read_b128 v[172:175], v233 offset:3072
	ds_read_b128 v[176:179], v233 offset:4096
	ds_read_b128 v[180:183], v233 offset:5120
	ds_read_b128 v[212:215], v233 offset:6144
	ds_read_b128 v[216:219], v233 offset:7168
	global_load_lds_dwordx4 v204, s[82:83]
	s_add_i32 m0, s19, 0xe000
	s_nop 0
	global_load_lds_dwordx4 v206, s[82:83]
	s_waitcnt vmcnt(8)
	s_waitcnt lgkmcnt(0)
	s_barrier
	s_setprio 1
	s_waitcnt lgkmcnt(0)
	v_mfma_f32_16x16x32_bf16 v[140:143], v[64:67], v[160:163], v[140:143]
	v_mfma_f32_16x16x32_bf16 v[140:143], v[68:71], v[164:167], v[140:143]
	v_mfma_f32_16x16x32_bf16 v[136:139], v[80:83], v[160:163], v[136:139]
	v_mfma_f32_16x16x32_bf16 v[136:139], v[84:87], v[164:167], v[136:139]
	v_mfma_f32_16x16x32_bf16 v[124:127], v[64:67], v[168:171], v[124:127]
	v_mfma_f32_16x16x32_bf16 v[124:127], v[68:71], v[172:175], v[124:127]
	v_mfma_f32_16x16x32_bf16 v[120:123], v[80:83], v[168:171], v[120:123]
	v_mfma_f32_16x16x32_bf16 v[120:123], v[84:87], v[172:175], v[120:123]
	v_mfma_f32_16x16x32_bf16 v[108:111], v[64:67], v[176:179], v[108:111]
	v_mfma_f32_16x16x32_bf16 v[108:111], v[68:71], v[180:183], v[108:111]
	v_mfma_f32_16x16x32_bf16 v[104:107], v[80:83], v[176:179], v[104:107]
	v_mfma_f32_16x16x32_bf16 v[104:107], v[84:87], v[180:183], v[104:107]
	v_mfma_f32_16x16x32_bf16 v[92:95], v[64:67], v[212:215], v[92:95]
	v_mfma_f32_16x16x32_bf16 v[92:95], v[68:71], v[216:219], v[92:95]
	v_mfma_f32_16x16x32_bf16 v[88:91], v[80:83], v[212:215], v[88:91]
	v_mfma_f32_16x16x32_bf16 v[88:91], v[84:87], v[216:219], v[88:91]
	s_setprio 0
	s_setprio 1
	v_mfma_f32_16x16x32_bf16 v[132:135], v[144:147], v[160:163], v[132:135]
	v_mfma_f32_16x16x32_bf16 v[132:135], v[148:151], v[164:167], v[132:135]
	v_mfma_f32_16x16x32_bf16 v[128:131], v[152:155], v[160:163], v[128:131]
	v_mfma_f32_16x16x32_bf16 v[128:131], v[156:159], v[164:167], v[128:131]
	v_mfma_f32_16x16x32_bf16 v[116:119], v[144:147], v[168:171], v[116:119]
	v_mfma_f32_16x16x32_bf16 v[116:119], v[148:151], v[172:175], v[116:119]
	v_mfma_f32_16x16x32_bf16 v[112:115], v[152:155], v[168:171], v[112:115]
	v_mfma_f32_16x16x32_bf16 v[112:115], v[156:159], v[172:175], v[112:115]
	v_mfma_f32_16x16x32_bf16 v[100:103], v[144:147], v[176:179], v[100:103]
	v_mfma_f32_16x16x32_bf16 v[100:103], v[148:151], v[180:183], v[100:103]
	v_mfma_f32_16x16x32_bf16 v[96:99], v[152:155], v[176:179], v[96:99]
	v_mfma_f32_16x16x32_bf16 v[96:99], v[156:159], v[180:183], v[96:99]
	v_mfma_f32_16x16x32_bf16 v[76:79], v[144:147], v[212:215], v[76:79]
	v_mfma_f32_16x16x32_bf16 v[76:79], v[148:151], v[216:219], v[76:79]
	v_mfma_f32_16x16x32_bf16 v[72:75], v[152:155], v[212:215], v[72:75]
	v_mfma_f32_16x16x32_bf16 v[72:75], v[156:159], v[216:219], v[72:75]
	s_setprio 0
	s_barrier
	s_add_i32 s54, s33, s18
	s_mov_b32 m0, s54
	ds_read_b128 v[160:163], v233 offset:16384
	ds_read_b128 v[164:167], v233 offset:17408
	ds_read_b128 v[168:171], v233 offset:18432
	ds_read_b128 v[172:175], v233 offset:19456
	ds_read_b128 v[176:179], v233 offset:20480
	ds_read_b128 v[180:183], v233 offset:21504
	ds_read_b128 v[212:215], v233 offset:22528
	ds_read_b128 v[216:219], v233 offset:23552
	global_load_lds_dwordx4 v196, s[96:97]
	s_add_i32 m0, s54, 0x2000
	s_add_u32 s54, s96, 0x4000
	s_addc_u32 s55, s97, 0
	s_add_i32 s56, s42, s18
	global_load_lds_dwordx4 v200, s[96:97]
	s_mov_b32 m0, s56
	s_nop 0
	global_load_lds_dwordx4 v196, s[54:55]
	s_add_i32 m0, s56, 0x2000
	s_nop 0
	global_load_lds_dwordx4 v200, s[54:55]
	v_lshl_add_u64 v[220:221], vcc, 0, v[194:195]
	s_mov_b32 m0, s19
	s_nop 0
	global_load_lds_dwordx4 v[220:221], off
	v_lshl_add_u64 v[220:221], vcc, 0, v[198:199]
	s_mov_b32 m0, s20
	s_nop 0
	global_load_lds_dwordx4 v[220:221], off
	s_waitcnt vmcnt(8)
	s_waitcnt lgkmcnt(0)
	s_barrier
	s_setprio 1
	s_waitcnt lgkmcnt(0)
	v_mfma_f32_16x16x32_bf16 v[60:63], v[64:67], v[160:163], v[60:63]
	v_mfma_f32_16x16x32_bf16 v[60:63], v[68:71], v[164:167], v[60:63]
	v_mfma_f32_16x16x32_bf16 v[56:59], v[80:83], v[160:163], v[56:59]
	v_mfma_f32_16x16x32_bf16 v[56:59], v[84:87], v[164:167], v[56:59]
	v_mfma_f32_16x16x32_bf16 v[44:47], v[64:67], v[168:171], v[44:47]
	v_mfma_f32_16x16x32_bf16 v[44:47], v[68:71], v[172:175], v[44:47]
	v_mfma_f32_16x16x32_bf16 v[40:43], v[80:83], v[168:171], v[40:43]
	v_mfma_f32_16x16x32_bf16 v[40:43], v[84:87], v[172:175], v[40:43]
	v_mfma_f32_16x16x32_bf16 v[28:31], v[64:67], v[176:179], v[28:31]
	v_mfma_f32_16x16x32_bf16 v[28:31], v[68:71], v[180:183], v[28:31]
	v_mfma_f32_16x16x32_bf16 v[24:27], v[80:83], v[176:179], v[24:27]
	v_mfma_f32_16x16x32_bf16 v[24:27], v[84:87], v[180:183], v[24:27]
	v_mfma_f32_16x16x32_bf16 v[12:15], v[64:67], v[212:215], v[12:15]
	v_mfma_f32_16x16x32_bf16 v[12:15], v[68:71], v[216:219], v[12:15]
	v_mfma_f32_16x16x32_bf16 v[8:11], v[80:83], v[212:215], v[8:11]
	v_mfma_f32_16x16x32_bf16 v[8:11], v[84:87], v[216:219], v[8:11]
	s_setprio 0
	s_setprio 1
	v_mfma_f32_16x16x32_bf16 v[52:55], v[144:147], v[160:163], v[52:55]
	v_mfma_f32_16x16x32_bf16 v[52:55], v[148:151], v[164:167], v[52:55]
	v_mfma_f32_16x16x32_bf16 v[48:51], v[152:155], v[160:163], v[48:51]
	v_mfma_f32_16x16x32_bf16 v[48:51], v[156:159], v[164:167], v[48:51]
	v_mfma_f32_16x16x32_bf16 v[36:39], v[144:147], v[168:171], v[36:39]
	v_mfma_f32_16x16x32_bf16 v[36:39], v[148:151], v[172:175], v[36:39]
	v_mfma_f32_16x16x32_bf16 v[32:35], v[152:155], v[168:171], v[32:35]
	v_mfma_f32_16x16x32_bf16 v[32:35], v[156:159], v[172:175], v[32:35]
	v_mfma_f32_16x16x32_bf16 v[20:23], v[144:147], v[176:179], v[20:23]
	v_mfma_f32_16x16x32_bf16 v[20:23], v[148:151], v[180:183], v[20:23]
	v_mfma_f32_16x16x32_bf16 v[16:19], v[152:155], v[176:179], v[16:19]
	v_mfma_f32_16x16x32_bf16 v[16:19], v[156:159], v[180:183], v[16:19]
	v_mfma_f32_16x16x32_bf16 v[4:7], v[144:147], v[212:215], v[4:7]
	v_mfma_f32_16x16x32_bf16 v[4:7], v[148:151], v[216:219], v[4:7]
	v_mfma_f32_16x16x32_bf16 v[0:3], v[152:155], v[212:215], v[0:3]
	v_mfma_f32_16x16x32_bf16 v[0:3], v[156:159], v[216:219], v[0:3]
	s_setprio 0
	s_barrier
; #define PG8_STAGE(bufoff, gbase, voff) do { _Pragma("unroll") for (int _i = 0; _i < 2; ++_i) \
;         __builtin_amdgcn_global_load_lds((const unsigned*)((const char*)(gbase) + (voff)[_i]), (LAS unsigned*)(lds + (bufoff) + ldsw + _i * 8192), 16, 0, 0); } while (0)
; #define PG8_LDA(dst, b, h) do { _Pragma("unroll") for (int m = 0; m < 4; ++m) _Pragma("unroll") for (int k = 0; k < 2; ++k) dst[m][k] = *(const LAS bf16x8*)(lds + PG8_SA(b, h) + aoff + m * 2048 + k * 1024); } while (0)
; #define PG8_LDB(dst, b, h) do { _Pragma("unroll") for (int n = 0; n < 2; ++n) _Pragma("unroll") for (int k = 0; k < 2; ++k) dst[n][k] = *(const LAS bf16x8*)(lds + PG8_SB(b, h) + boff + n * 2048 + k * 1024); } while (0)
; #define PG8_MMA(ai, bj, At, Bt) do { __builtin_amdgcn_s_setprio(1); _Pragma("unroll") for (int m = 0; m < 4; ++m) _Pragma("unroll") for (int n = 0; n < 2; ++n) _Pragma("unroll") for (int k = 0; k < 2; ++k) \
;         acc[ai][bj][m][n] = __builtin_amdgcn_mfma_f32_16x16x32_bf16(Bt[n][k], At[m][k], acc[ai][bj][m][n], 0, 0, 0); __builtin_amdgcn_s_setprio(0); } while (0)
; #define PG8_WAIT_V(n) asm volatile("s_waitcnt vmcnt(" #n ")" ::: "memory")
; #define PG8_WAIT_L(n) asm volatile("s_waitcnt lgkmcnt(" #n ")" ::: "memory")
; #define PG8_BAR __builtin_amdgcn_s_barrier()
; #define PG8_SCHED __builtin_amdgcn_sched_barrier(0)
; template <bool ALIGN_EPI, class Epi, class Sched>
; __device__ __forceinline__ void gemm_phase(LAS unsigned char* lds, const int lda, const int ldb, const int K, const Sched& S, const Epi& E, const size_t kstepA = (size_t)(BK * 2), const size_t kstepB = (size_t)(BK * 2)) {
;     ...
;             PG8_LDB(B0, 1, 0); PG8_LDB(B1, 1, 1); PG8_SCHED; PG8_LDA(At, 1, 0); PG8_STAGE(PG8_SA(0, 1), a2 + hstepA, voffA);
;             PG8_WAIT_V(8); PG8_WAIT_L(0); PG8_BAR; PG8_MMA(0, 0, At, B0); PG8_MMA(0, 1, At, B1); PG8_BAR; PG8_SCHED;
;             PG8_LDA(At, 1, 1); PG8_STAGE(PG8_SB(1, 0), b3, voffB); PG8_STAGE(PG8_SB(1, 1), b3 + hstepB, voffB); PG8_STAGE(PG8_SA(1, 0), a3, voffA);
;             PG8_WAIT_V(8); PG8_WAIT_L(0); PG8_BAR; PG8_MMA(1, 0, At, B0); PG8_MMA(1, 1, At, B1); PG8_BAR; PG8_SCHED;
;         }
	s_add_i32 s56, 0, 0x18000
	s_add_i32 s57, 0, 0x1c000
	v_add_u32_e32 v84, s56, v191
	v_add_u32_e32 v156, s57, v191
	ds_read_b128 v[64:67], v84
	ds_read_b128 v[68:71], v84 offset:1024
	ds_read_b128 v[80:83], v84 offset:2048
	ds_read_b128 v[84:87], v84 offset:3072
	ds_read_b128 v[144:147], v156
	ds_read_b128 v[148:151], v156 offset:1024
	ds_read_b128 v[152:155], v156 offset:2048
	ds_read_b128 v[156:159], v156 offset:3072
	s_add_u32 s54, vcc_lo, 0x4000
	s_addc_u32 s55, vcc_hi, 0
	s_mov_b32 m0, s21
	ds_read_b128 v[160:163], v233 offset:32768
	ds_read_b128 v[164:167], v233 offset:33792
	ds_read_b128 v[168:171], v233 offset:34816
	ds_read_b128 v[172:175], v233 offset:35840
	ds_read_b128 v[176:179], v233 offset:36864
	ds_read_b128 v[180:183], v233 offset:37888
	ds_read_b128 v[212:215], v233 offset:38912
	ds_read_b128 v[216:219], v233 offset:39936
	global_load_lds_dwordx4 v194, s[54:55]
	s_mov_b32 m0, s22
	s_nop 0
	global_load_lds_dwordx4 v198, s[54:55]
	s_waitcnt vmcnt(8)
	s_waitcnt lgkmcnt(0)
	s_barrier
	s_setprio 1
	s_waitcnt lgkmcnt(0)
	v_mfma_f32_16x16x32_bf16 v[140:143], v[64:67], v[160:163], v[140:143]
	v_mfma_f32_16x16x32_bf16 v[140:143], v[68:71], v[164:167], v[140:143]
	v_mfma_f32_16x16x32_bf16 v[136:139], v[80:83], v[160:163], v[136:139]
	v_mfma_f32_16x16x32_bf16 v[136:139], v[84:87], v[164:167], v[136:139]
	v_mfma_f32_16x16x32_bf16 v[124:127], v[64:67], v[168:171], v[124:127]
	v_mfma_f32_16x16x32_bf16 v[124:127], v[68:71], v[172:175], v[124:127]
	v_mfma_f32_16x16x32_bf16 v[120:123], v[80:83], v[168:171], v[120:123]
	v_mfma_f32_16x16x32_bf16 v[120:123], v[84:87], v[172:175], v[120:123]
	v_mfma_f32_16x16x32_bf16 v[108:111], v[64:67], v[176:179], v[108:111]
	v_mfma_f32_16x16x32_bf16 v[108:111], v[68:71], v[180:183], v[108:111]
	v_mfma_f32_16x16x32_bf16 v[104:107], v[80:83], v[176:179], v[104:107]
	v_mfma_f32_16x16x32_bf16 v[104:107], v[84:87], v[180:183], v[104:107]
	v_mfma_f32_16x16x32_bf16 v[92:95], v[64:67], v[212:215], v[92:95]
	v_mfma_f32_16x16x32_bf16 v[92:95], v[68:71], v[216:219], v[92:95]
	v_mfma_f32_16x16x32_bf16 v[88:91], v[80:83], v[212:215], v[88:91]
	v_mfma_f32_16x16x32_bf16 v[88:91], v[84:87], v[216:219], v[88:91]
	s_setprio 0
	s_setprio 1
	v_mfma_f32_16x16x32_bf16 v[132:135], v[144:147], v[160:163], v[132:135]
	v_mfma_f32_16x16x32_bf16 v[132:135], v[148:151], v[164:167], v[132:135]
	v_mfma_f32_16x16x32_bf16 v[128:131], v[152:155], v[160:163], v[128:131]
	v_mfma_f32_16x16x32_bf16 v[128:131], v[156:159], v[164:167], v[128:131]
	v_mfma_f32_16x16x32_bf16 v[116:119], v[144:147], v[168:171], v[116:119]
	v_mfma_f32_16x16x32_bf16 v[116:119], v[148:151], v[172:175], v[116:119]
	v_mfma_f32_16x16x32_bf16 v[112:115], v[152:155], v[168:171], v[112:115]
	v_mfma_f32_16x16x32_bf16 v[112:115], v[156:159], v[172:175], v[112:115]
	v_mfma_f32_16x16x32_bf16 v[100:103], v[144:147], v[176:179], v[100:103]
	v_mfma_f32_16x16x32_bf16 v[100:103], v[148:151], v[180:183], v[100:103]
	v_mfma_f32_16x16x32_bf16 v[96:99], v[152:155], v[176:179], v[96:99]
	v_mfma_f32_16x16x32_bf16 v[96:99], v[156:159], v[180:183], v[96:99]
	v_mfma_f32_16x16x32_bf16 v[76:79], v[144:147], v[212:215], v[76:79]
	v_mfma_f32_16x16x32_bf16 v[76:79], v[148:151], v[216:219], v[76:79]
	v_mfma_f32_16x16x32_bf16 v[72:75], v[152:155], v[212:215], v[72:75]
	v_mfma_f32_16x16x32_bf16 v[72:75], v[156:159], v[216:219], v[72:75]
	s_setprio 0
	s_barrier
	s_add_u32 s54, s96, 0x40000
	s_addc_u32 s55, s97, 0
	s_add_i32 s56, s56, s18
	s_mov_b32 m0, s56
	ds_read_b128 v[160:163], v233 offset:49152
	ds_read_b128 v[164:167], v233 offset:50176
	ds_read_b128 v[168:171], v233 offset:51200
	ds_read_b128 v[172:175], v233 offset:52224
	ds_read_b128 v[176:179], v233 offset:53248
	ds_read_b128 v[180:183], v233 offset:54272
	ds_read_b128 v[212:215], v233 offset:55296
	ds_read_b128 v[216:219], v233 offset:56320
	global_load_lds_dwordx4 v196, s[54:55]
	s_add_i32 m0, s56, 0x2000
	s_nop 0
	global_load_lds_dwordx4 v200, s[54:55]
	s_add_u32 s54, s96, 0x44000
	s_addc_u32 s55, s97, 0
	s_add_i32 s56, s57, s18
	s_mov_b32 m0, s56
	s_nop 0
	global_load_lds_dwordx4 v196, s[54:55]
	s_add_i32 m0, s56, 0x2000
	s_nop 0
	global_load_lds_dwordx4 v200, s[54:55]
	s_mov_b32 m0, s30
	s_nop 0
	global_load_lds_dwordx4 v194, s[94:95]
	s_mov_b32 m0, s31
	s_nop 0
	global_load_lds_dwordx4 v198, s[94:95]
	s_waitcnt vmcnt(8)
	s_waitcnt lgkmcnt(0)
	s_barrier
	s_setprio 1
	s_waitcnt lgkmcnt(0)
	v_mfma_f32_16x16x32_bf16 v[60:63], v[64:67], v[160:163], v[60:63]
	v_mfma_f32_16x16x32_bf16 v[60:63], v[68:71], v[164:167], v[60:63]
	v_mfma_f32_16x16x32_bf16 v[56:59], v[80:83], v[160:163], v[56:59]
	v_mfma_f32_16x16x32_bf16 v[56:59], v[84:87], v[164:167], v[56:59]
	v_mfma_f32_16x16x32_bf16 v[44:47], v[64:67], v[168:171], v[44:47]
	v_mfma_f32_16x16x32_bf16 v[44:47], v[68:71], v[172:175], v[44:47]
	v_mfma_f32_16x16x32_bf16 v[40:43], v[80:83], v[168:171], v[40:43]
	v_mfma_f32_16x16x32_bf16 v[40:43], v[84:87], v[172:175], v[40:43]
	v_mfma_f32_16x16x32_bf16 v[28:31], v[64:67], v[176:179], v[28:31]
	v_mfma_f32_16x16x32_bf16 v[28:31], v[68:71], v[180:183], v[28:31]
	v_mfma_f32_16x16x32_bf16 v[24:27], v[80:83], v[176:179], v[24:27]
	v_mfma_f32_16x16x32_bf16 v[24:27], v[84:87], v[180:183], v[24:27]
	v_mfma_f32_16x16x32_bf16 v[12:15], v[64:67], v[212:215], v[12:15]
	v_mfma_f32_16x16x32_bf16 v[12:15], v[68:71], v[216:219], v[12:15]
	v_mfma_f32_16x16x32_bf16 v[8:11], v[80:83], v[212:215], v[8:11]
	v_mfma_f32_16x16x32_bf16 v[8:11], v[84:87], v[216:219], v[8:11]
	s_setprio 0
	s_setprio 1
	v_mfma_f32_16x16x32_bf16 v[52:55], v[144:147], v[160:163], v[52:55]
	v_mfma_f32_16x16x32_bf16 v[52:55], v[148:151], v[164:167], v[52:55]
	v_mfma_f32_16x16x32_bf16 v[48:51], v[152:155], v[160:163], v[48:51]
	v_mfma_f32_16x16x32_bf16 v[48:51], v[156:159], v[164:167], v[48:51]
	v_mfma_f32_16x16x32_bf16 v[36:39], v[144:147], v[168:171], v[36:39]
	v_mfma_f32_16x16x32_bf16 v[36:39], v[148:151], v[172:175], v[36:39]
	v_mfma_f32_16x16x32_bf16 v[32:35], v[152:155], v[168:171], v[32:35]
	v_mfma_f32_16x16x32_bf16 v[32:35], v[156:159], v[172:175], v[32:35]
	v_mfma_f32_16x16x32_bf16 v[20:23], v[144:147], v[176:179], v[20:23]
	v_mfma_f32_16x16x32_bf16 v[20:23], v[148:151], v[180:183], v[20:23]
	v_mfma_f32_16x16x32_bf16 v[16:19], v[152:155], v[176:179], v[16:19]
	v_mfma_f32_16x16x32_bf16 v[16:19], v[156:159], v[180:183], v[16:19]
	v_mfma_f32_16x16x32_bf16 v[4:7], v[144:147], v[212:215], v[4:7]
	v_mfma_f32_16x16x32_bf16 v[4:7], v[148:151], v[216:219], v[4:7]
	v_mfma_f32_16x16x32_bf16 v[0:3], v[152:155], v[212:215], v[0:3]
	v_mfma_f32_16x16x32_bf16 v[0:3], v[156:159], v[216:219], v[0:3]
	s_setprio 0
	s_barrier
	s_add_i32 s51, s51, 2
	s_add_u32 s13, s13, 0x80000
	s_addc_u32 s50, s50, 0
	s_add_u32 s82, s82, 0x400000
	s_addc_u32 s83, s83, 0
	s_cmpk_gt_u32 s51, 0x55
	s_cbranch_scc0 .LBB0_218
	s_and_b64 vcc, exec, s[84:85]
	s_cbranch_vccz .LBB0_221
	s_barrier

; #define PG8_STAGE(bufoff, gbase, voff) do { _Pragma("unroll") for (int _i = 0; _i < 2; ++_i) \
;         __builtin_amdgcn_global_load_lds((const unsigned*)((const char*)(gbase) + (voff)[_i]), (LAS unsigned*)(lds + (bufoff) + ldsw + _i * 8192), 16, 0, 0); } while (0)
; #define PG8_LDA(dst, b, h) do { _Pragma("unroll") for (int m = 0; m < 4; ++m) _Pragma("unroll") for (int k = 0; k < 2; ++k) dst[m][k] = *(const LAS bf16x8*)(lds + PG8_SA(b, h) + aoff + m * 2048 + k * 1024); } while (0)
; #define PG8_LDB(dst, b, h) do { _Pragma("unroll") for (int n = 0; n < 2; ++n) _Pragma("unroll") for (int k = 0; k < 2; ++k) dst[n][k] = *(const LAS bf16x8*)(lds + PG8_SB(b, h) + boff + n * 2048 + k * 1024); } while (0)
; #define PG8_MMA(ai, bj, At, Bt) do { __builtin_amdgcn_s_setprio(1); _Pragma("unroll") for (int m = 0; m < 4; ++m) _Pragma("unroll") for (int n = 0; n < 2; ++n) _Pragma("unroll") for (int k = 0; k < 2; ++k) \
;         acc[ai][bj][m][n] = __builtin_amdgcn_mfma_f32_16x16x32_bf16(Bt[n][k], At[m][k], acc[ai][bj][m][n], 0, 0, 0); __builtin_amdgcn_s_setprio(0); } while (0)
; #define PG8_WAIT_V(n) asm volatile("s_waitcnt vmcnt(" #n ")" ::: "memory")
; #define PG8_WAIT_L(n) asm volatile("s_waitcnt lgkmcnt(" #n ")" ::: "memory")
; template <bool ALIGN_EPI, class Epi, class Sched>
; __device__ __forceinline__ void gemm_phase(LAS unsigned char* lds, const int lda, const int ldb, const int K, const Sched& S, const Epi& E, const size_t kstepA = (size_t)(BK * 2), const size_t kstepB = (size_t)(BK * 2)) {
;     ...
;         for (int t = 0; t < nt; t += 2) {
;             const bool last = (t == nt - 2);
;             const char* a1 = cA + (size_t)(t + 1) * kstepA;
;             const char* a2 = last ? nA : cA + (size_t)(t + 2) * kstepA; const char* b2 = last ? nB : cB + (size_t)(t + 2) * kstep;
;             const char* a3 = a2 + kstepA; const char* b3 = b2 + kstep;
;             PG8_LDB(B0, 0, 0); PG8_LDB(B1, 0, 1); PG8_SCHED; PG8_LDA(At, 0, 0); PG8_STAGE(PG8_SA(1, 1), a1 + hstepA, voffA);
;             PG8_WAIT_V(8); PG8_WAIT_L(0); PG8_BAR; PG8_MMA(0, 0, At, B0); PG8_MMA(0, 1, At, B1); PG8_BAR; PG8_SCHED;
;             PG8_LDA(At, 0, 1); PG8_STAGE(PG8_SB(0, 0), b2, voffB); PG8_STAGE(PG8_SB(0, 1), b2 + hstepB, voffB); PG8_STAGE(PG8_SA(0, 0), a2, voffA);
;             PG8_WAIT_V(8); PG8_WAIT_L(0); PG8_BAR; PG8_MMA(1, 0, At, B0); PG8_MMA(1, 1, At, B1); PG8_BAR; PG8_SCHED;
.LBB0_347:
	ds_read_b128 v[158:161], v195
	ds_read_b128 v[162:165], v195 offset:1024
	ds_read_b128 v[166:169], v195 offset:2048
	ds_read_b128 v[198:201], v195 offset:3072
	ds_read_b128 v[202:205], v196
	ds_read_b128 v[206:209], v196 offset:1024
	ds_read_b128 v[210:213], v196 offset:2048
	ds_read_b128 v[214:217], v196 offset:3072
	s_add_u32 s59, s16, 0x1fc000
	s_addc_u32 s60, s17, 0
	s_cmp_eq_u32 s58, 28
	s_cselect_b32 s94, s6, s59
	s_cselect_b32 s95, s7, s60
	s_cselect_b32 s92, s14, s55
	s_cselect_b32 s93, s15, s57
	s_add_u32 s82, s94, 0x200000
	s_addc_u32 s83, s95, 0
	s_add_i32 m0, s20, 0xc000
	ds_read_b128 v[218:221], v193
	ds_read_b128 v[222:225], v193 offset:1024
	ds_read_b128 v[226:229], v193 offset:2048
	ds_read_b128 v[230:233], v193 offset:3072
	ds_read_b128 v[234:237], v193 offset:4096
	ds_read_b128 v[238:241], v193 offset:5120
	ds_read_b128 v[242:245], v193 offset:6144
	ds_read_b128 v[246:249], v193 offset:7168
	global_load_lds_dwordx4 v150, s[16:17]
	s_add_i32 m0, s20, 0xe000
	s_nop 0
	global_load_lds_dwordx4 v152, s[16:17]
	s_waitcnt vmcnt(8)
	s_waitcnt lgkmcnt(0)
	s_barrier
	s_setprio 1
	s_waitcnt lgkmcnt(0)
	v_mfma_f32_16x16x32_bf16 v[124:127], v[158:161], v[218:221], v[124:127]
	v_mfma_f32_16x16x32_bf16 v[124:127], v[162:165], v[222:225], v[124:127]
	v_mfma_f32_16x16x32_bf16 v[120:123], v[166:169], v[218:221], v[120:123]
	v_mfma_f32_16x16x32_bf16 v[120:123], v[198:201], v[222:225], v[120:123]
	v_mfma_f32_16x16x32_bf16 v[108:111], v[158:161], v[226:229], v[108:111]
	v_mfma_f32_16x16x32_bf16 v[108:111], v[162:165], v[230:233], v[108:111]
	v_mfma_f32_16x16x32_bf16 v[104:107], v[166:169], v[226:229], v[104:107]
	v_mfma_f32_16x16x32_bf16 v[104:107], v[198:201], v[230:233], v[104:107]
	v_mfma_f32_16x16x32_bf16 v[92:95], v[158:161], v[234:237], v[92:95]
	v_mfma_f32_16x16x32_bf16 v[92:95], v[162:165], v[238:241], v[92:95]
	v_mfma_f32_16x16x32_bf16 v[88:91], v[166:169], v[234:237], v[88:91]
	v_mfma_f32_16x16x32_bf16 v[88:91], v[198:201], v[238:241], v[88:91]
	v_mfma_f32_16x16x32_bf16 v[76:79], v[158:161], v[242:245], v[76:79]
	v_mfma_f32_16x16x32_bf16 v[76:79], v[162:165], v[246:249], v[76:79]
	v_mfma_f32_16x16x32_bf16 v[72:75], v[166:169], v[242:245], v[72:75]
	v_mfma_f32_16x16x32_bf16 v[72:75], v[198:201], v[246:249], v[72:75]
	s_setprio 0
	s_setprio 1
	v_mfma_f32_16x16x32_bf16 v[116:119], v[202:205], v[218:221], v[116:119]
	v_mfma_f32_16x16x32_bf16 v[116:119], v[206:209], v[222:225], v[116:119]
	v_mfma_f32_16x16x32_bf16 v[112:115], v[210:213], v[218:221], v[112:115]
	v_mfma_f32_16x16x32_bf16 v[112:115], v[214:217], v[222:225], v[112:115]
	v_mfma_f32_16x16x32_bf16 v[100:103], v[202:205], v[226:229], v[100:103]
	v_mfma_f32_16x16x32_bf16 v[100:103], v[206:209], v[230:233], v[100:103]
	v_mfma_f32_16x16x32_bf16 v[96:99], v[210:213], v[226:229], v[96:99]
	v_mfma_f32_16x16x32_bf16 v[96:99], v[214:217], v[230:233], v[96:99]
	v_mfma_f32_16x16x32_bf16 v[84:87], v[202:205], v[234:237], v[84:87]
	v_mfma_f32_16x16x32_bf16 v[84:87], v[206:209], v[238:241], v[84:87]
	v_mfma_f32_16x16x32_bf16 v[80:83], v[210:213], v[234:237], v[80:83]
	v_mfma_f32_16x16x32_bf16 v[80:83], v[214:217], v[238:241], v[80:83]
	v_mfma_f32_16x16x32_bf16 v[68:71], v[202:205], v[242:245], v[68:71]
	v_mfma_f32_16x16x32_bf16 v[68:71], v[206:209], v[246:249], v[68:71]
	v_mfma_f32_16x16x32_bf16 v[64:67], v[210:213], v[242:245], v[64:67]
	v_mfma_f32_16x16x32_bf16 v[64:67], v[214:217], v[246:249], v[64:67]
	s_setprio 0
	s_barrier
	s_add_i32 s59, s42, s19
	s_mov_b32 m0, s59
	ds_read_b128 v[218:221], v193 offset:16384
	ds_read_b128 v[222:225], v193 offset:17408
	ds_read_b128 v[226:229], v193 offset:18432
	ds_read_b128 v[230:233], v193 offset:19456
	ds_read_b128 v[234:237], v193 offset:20480
	ds_read_b128 v[238:241], v193 offset:21504
	ds_read_b128 v[242:245], v193 offset:22528
	ds_read_b128 v[246:249], v193 offset:23552
	global_load_lds_dwordx4 v130, s[92:93]
	s_add_i32 m0, s59, 0x2000
	s_add_u32 s60, s92, 0x4000
	s_addc_u32 s61, s93, 0
	s_add_i32 s59, s43, s19
	global_load_lds_dwordx4 v134, s[92:93]
	s_mov_b32 m0, s59
	s_nop 0
	global_load_lds_dwordx4 v130, s[60:61]
	s_add_i32 m0, s59, 0x2000
	s_nop 0
	global_load_lds_dwordx4 v134, s[60:61]
	s_mov_b32 m0, s20
	s_nop 0
	global_load_lds_dwordx4 v128, s[94:95]
	s_mov_b32 m0, s21
	s_nop 0
	global_load_lds_dwordx4 v132, s[94:95]
	s_waitcnt vmcnt(8)
	s_waitcnt lgkmcnt(0)
	s_barrier
	s_setprio 1
	s_waitcnt lgkmcnt(0)
	v_mfma_f32_16x16x32_bf16 v[60:63], v[158:161], v[218:221], v[60:63]
	v_mfma_f32_16x16x32_bf16 v[60:63], v[162:165], v[222:225], v[60:63]
	v_mfma_f32_16x16x32_bf16 v[56:59], v[166:169], v[218:221], v[56:59]
	v_mfma_f32_16x16x32_bf16 v[56:59], v[198:201], v[222:225], v[56:59]
	v_mfma_f32_16x16x32_bf16 v[44:47], v[158:161], v[226:229], v[44:47]
	v_mfma_f32_16x16x32_bf16 v[44:47], v[162:165], v[230:233], v[44:47]
	v_mfma_f32_16x16x32_bf16 v[40:43], v[166:169], v[226:229], v[40:43]
	v_mfma_f32_16x16x32_bf16 v[40:43], v[198:201], v[230:233], v[40:43]
	v_mfma_f32_16x16x32_bf16 v[28:31], v[158:161], v[234:237], v[28:31]
	v_mfma_f32_16x16x32_bf16 v[28:31], v[162:165], v[238:241], v[28:31]
	v_mfma_f32_16x16x32_bf16 v[24:27], v[166:169], v[234:237], v[24:27]
	v_mfma_f32_16x16x32_bf16 v[24:27], v[198:201], v[238:241], v[24:27]
	v_mfma_f32_16x16x32_bf16 v[12:15], v[158:161], v[242:245], v[12:15]
	v_mfma_f32_16x16x32_bf16 v[12:15], v[162:165], v[246:249], v[12:15]
	v_mfma_f32_16x16x32_bf16 v[8:11], v[166:169], v[242:245], v[8:11]
	v_mfma_f32_16x16x32_bf16 v[8:11], v[198:201], v[246:249], v[8:11]
	s_setprio 0
	s_setprio 1
	v_mfma_f32_16x16x32_bf16 v[52:55], v[202:205], v[218:221], v[52:55]
	v_mfma_f32_16x16x32_bf16 v[52:55], v[206:209], v[222:225], v[52:55]
	v_mfma_f32_16x16x32_bf16 v[48:51], v[210:213], v[218:221], v[48:51]
	v_mfma_f32_16x16x32_bf16 v[48:51], v[214:217], v[222:225], v[48:51]
	v_mfma_f32_16x16x32_bf16 v[36:39], v[202:205], v[226:229], v[36:39]
	v_mfma_f32_16x16x32_bf16 v[36:39], v[206:209], v[230:233], v[36:39]
	v_mfma_f32_16x16x32_bf16 v[32:35], v[210:213], v[226:229], v[32:35]
	v_mfma_f32_16x16x32_bf16 v[32:35], v[214:217], v[230:233], v[32:35]
	v_mfma_f32_16x16x32_bf16 v[20:23], v[202:205], v[234:237], v[20:23]
	v_mfma_f32_16x16x32_bf16 v[20:23], v[206:209], v[238:241], v[20:23]
	v_mfma_f32_16x16x32_bf16 v[16:19], v[210:213], v[234:237], v[16:19]
	v_mfma_f32_16x16x32_bf16 v[16:19], v[214:217], v[238:241], v[16:19]
	v_mfma_f32_16x16x32_bf16 v[4:7], v[202:205], v[242:245], v[4:7]
	v_mfma_f32_16x16x32_bf16 v[4:7], v[206:209], v[246:249], v[4:7]
	v_mfma_f32_16x16x32_bf16 v[0:3], v[210:213], v[242:245], v[0:3]
	v_mfma_f32_16x16x32_bf16 v[0:3], v[214:217], v[246:249], v[0:3]
	s_setprio 0
	s_barrier
; #define PG8_STAGE(bufoff, gbase, voff) do { _Pragma("unroll") for (int _i = 0; _i < 2; ++_i) \
;         __builtin_amdgcn_global_load_lds((const unsigned*)((const char*)(gbase) + (voff)[_i]), (LAS unsigned*)(lds + (bufoff) + ldsw + _i * 8192), 16, 0, 0); } while (0)
; #define PG8_LDA(dst, b, h) do { _Pragma("unroll") for (int m = 0; m < 4; ++m) _Pragma("unroll") for (int k = 0; k < 2; ++k) dst[m][k] = *(const LAS bf16x8*)(lds + PG8_SA(b, h) + aoff + m * 2048 + k * 1024); } while (0)
; #define PG8_LDB(dst, b, h) do { _Pragma("unroll") for (int n = 0; n < 2; ++n) _Pragma("unroll") for (int k = 0; k < 2; ++k) dst[n][k] = *(const LAS bf16x8*)(lds + PG8_SB(b, h) + boff + n * 2048 + k * 1024); } while (0)
; #define PG8_MMA(ai, bj, At, Bt) do { __builtin_amdgcn_s_setprio(1); _Pragma("unroll") for (int m = 0; m < 4; ++m) _Pragma("unroll") for (int n = 0; n < 2; ++n) _Pragma("unroll") for (int k = 0; k < 2; ++k) \
;         acc[ai][bj][m][n] = __builtin_amdgcn_mfma_f32_16x16x32_bf16(Bt[n][k], At[m][k], acc[ai][bj][m][n], 0, 0, 0); __builtin_amdgcn_s_setprio(0); } while (0)
; #define PG8_WAIT_V(n) asm volatile("s_waitcnt vmcnt(" #n ")" ::: "memory")
; #define PG8_WAIT_L(n) asm volatile("s_waitcnt lgkmcnt(" #n ")" ::: "memory")
; #define PG8_BAR __builtin_amdgcn_s_barrier()
; #define PG8_SCHED __builtin_amdgcn_sched_barrier(0)
; template <bool ALIGN_EPI, class Epi, class Sched>
; __device__ __forceinline__ void gemm_phase(LAS unsigned char* lds, const int lda, const int ldb, const int K, const Sched& S, const Epi& E, const size_t kstepA = (size_t)(BK * 2), const size_t kstepB = (size_t)(BK * 2)) {
;     ...
;             PG8_LDB(B0, 1, 0); PG8_LDB(B1, 1, 1); PG8_SCHED; PG8_LDA(At, 1, 0); PG8_STAGE(PG8_SA(0, 1), a2 + hstepA, voffA);
;             PG8_WAIT_V(8); PG8_WAIT_L(0); PG8_BAR; PG8_MMA(0, 0, At, B0); PG8_MMA(0, 1, At, B1); PG8_BAR; PG8_SCHED;
;             PG8_LDA(At, 1, 1); PG8_STAGE(PG8_SB(1, 0), b3, voffB); PG8_STAGE(PG8_SB(1, 1), b3 + hstepB, voffB); PG8_STAGE(PG8_SA(1, 0), a3, voffA);
;             PG8_WAIT_V(8); PG8_WAIT_L(0); PG8_BAR; PG8_MMA(1, 0, At, B0); PG8_MMA(1, 1, At, B1); PG8_BAR; PG8_SCHED;
;         }
;         if constexpr (ALIGN_EPI) { if (wr == 0) PG8_BAR; }
	s_add_i32 s59, 0, 0x18000
	v_add_u32_e32 v136, s59, v141
	s_add_i32 s64, 0, 0x1c000
	ds_read_b128 v[158:161], v136
	ds_read_b128 v[162:165], v136 offset:1024
	ds_read_b128 v[166:169], v136 offset:2048
	ds_read_b128 v[198:201], v136 offset:3072
	v_add_u32_e32 v136, s64, v141
	ds_read_b128 v[202:205], v136
	ds_read_b128 v[206:209], v136 offset:1024
	ds_read_b128 v[210:213], v136 offset:2048
	ds_read_b128 v[214:217], v136 offset:3072
	s_add_u32 s60, s94, 0x4000
	s_addc_u32 s61, s95, 0
	s_mov_b32 m0, s22
	ds_read_b128 v[218:221], v193 offset:32768
	ds_read_b128 v[222:225], v193 offset:33792
	ds_read_b128 v[226:229], v193 offset:34816
	ds_read_b128 v[230:233], v193 offset:35840
	ds_read_b128 v[234:237], v193 offset:36864
	ds_read_b128 v[238:241], v193 offset:37888
	ds_read_b128 v[242:245], v193 offset:38912
	ds_read_b128 v[246:249], v193 offset:39936
	global_load_lds_dwordx4 v128, s[60:61]
	s_mov_b32 m0, s23
	s_nop 0
	global_load_lds_dwordx4 v132, s[60:61]
	s_waitcnt vmcnt(8)
	s_waitcnt lgkmcnt(0)
	s_barrier
	s_setprio 1
	s_waitcnt lgkmcnt(0)
	v_mfma_f32_16x16x32_bf16 v[124:127], v[158:161], v[218:221], v[124:127]
	v_mfma_f32_16x16x32_bf16 v[124:127], v[162:165], v[222:225], v[124:127]
	v_mfma_f32_16x16x32_bf16 v[120:123], v[166:169], v[218:221], v[120:123]
	v_mfma_f32_16x16x32_bf16 v[120:123], v[198:201], v[222:225], v[120:123]
	v_mfma_f32_16x16x32_bf16 v[108:111], v[158:161], v[226:229], v[108:111]
	v_mfma_f32_16x16x32_bf16 v[108:111], v[162:165], v[230:233], v[108:111]
	v_mfma_f32_16x16x32_bf16 v[104:107], v[166:169], v[226:229], v[104:107]
	v_mfma_f32_16x16x32_bf16 v[104:107], v[198:201], v[230:233], v[104:107]
	v_mfma_f32_16x16x32_bf16 v[92:95], v[158:161], v[234:237], v[92:95]
	v_mfma_f32_16x16x32_bf16 v[92:95], v[162:165], v[238:241], v[92:95]
	v_mfma_f32_16x16x32_bf16 v[88:91], v[166:169], v[234:237], v[88:91]
	v_mfma_f32_16x16x32_bf16 v[88:91], v[198:201], v[238:241], v[88:91]
	v_mfma_f32_16x16x32_bf16 v[76:79], v[158:161], v[242:245], v[76:79]
	v_mfma_f32_16x16x32_bf16 v[76:79], v[162:165], v[246:249], v[76:79]
	v_mfma_f32_16x16x32_bf16 v[72:75], v[166:169], v[242:245], v[72:75]
	v_mfma_f32_16x16x32_bf16 v[72:75], v[198:201], v[246:249], v[72:75]
	s_setprio 0
	s_setprio 1
	v_mfma_f32_16x16x32_bf16 v[116:119], v[202:205], v[218:221], v[116:119]
	v_mfma_f32_16x16x32_bf16 v[116:119], v[206:209], v[222:225], v[116:119]
	v_mfma_f32_16x16x32_bf16 v[112:115], v[210:213], v[218:221], v[112:115]
	v_mfma_f32_16x16x32_bf16 v[112:115], v[214:217], v[222:225], v[112:115]
	v_mfma_f32_16x16x32_bf16 v[100:103], v[202:205], v[226:229], v[100:103]
	v_mfma_f32_16x16x32_bf16 v[100:103], v[206:209], v[230:233], v[100:103]
	v_mfma_f32_16x16x32_bf16 v[96:99], v[210:213], v[226:229], v[96:99]
	v_mfma_f32_16x16x32_bf16 v[96:99], v[214:217], v[230:233], v[96:99]
	v_mfma_f32_16x16x32_bf16 v[84:87], v[202:205], v[234:237], v[84:87]
	v_mfma_f32_16x16x32_bf16 v[84:87], v[206:209], v[238:241], v[84:87]
	v_mfma_f32_16x16x32_bf16 v[80:83], v[210:213], v[234:237], v[80:83]
	v_mfma_f32_16x16x32_bf16 v[80:83], v[214:217], v[238:241], v[80:83]
	v_mfma_f32_16x16x32_bf16 v[68:71], v[202:205], v[242:245], v[68:71]
	v_mfma_f32_16x16x32_bf16 v[68:71], v[206:209], v[246:249], v[68:71]
	v_mfma_f32_16x16x32_bf16 v[64:67], v[210:213], v[242:245], v[64:67]
	v_mfma_f32_16x16x32_bf16 v[64:67], v[214:217], v[246:249], v[64:67]
	s_setprio 0
	s_barrier
	s_add_u32 s60, s92, 0x80000
	s_addc_u32 s61, s93, 0
	s_add_i32 s59, s59, s19
	s_mov_b32 m0, s59
	ds_read_b128 v[218:221], v193 offset:49152
	ds_read_b128 v[222:225], v193 offset:50176
	ds_read_b128 v[226:229], v193 offset:51200
	ds_read_b128 v[230:233], v193 offset:52224
	ds_read_b128 v[234:237], v193 offset:53248
	ds_read_b128 v[238:241], v193 offset:54272
	ds_read_b128 v[242:245], v193 offset:55296
	ds_read_b128 v[246:249], v193 offset:56320
	global_load_lds_dwordx4 v130, s[60:61]
	s_add_i32 m0, s59, 0x2000
	s_nop 0
	global_load_lds_dwordx4 v134, s[60:61]
	s_add_u32 s60, s92, 0x84000
	s_addc_u32 s61, s93, 0
	s_add_i32 s59, s64, s19
	s_mov_b32 m0, s59
	s_nop 0
	global_load_lds_dwordx4 v130, s[60:61]
	s_add_i32 m0, s59, 0x2000
	s_nop 0
	global_load_lds_dwordx4 v134, s[60:61]
	s_mov_b32 m0, s30
	s_nop 0
	global_load_lds_dwordx4 v128, s[82:83]
	s_mov_b32 m0, s31
	s_nop 0
	global_load_lds_dwordx4 v132, s[82:83]
	s_waitcnt vmcnt(8)
	s_waitcnt lgkmcnt(0)
	s_barrier
	s_setprio 1
	s_waitcnt lgkmcnt(0)
	v_mfma_f32_16x16x32_bf16 v[60:63], v[158:161], v[218:221], v[60:63]
	v_mfma_f32_16x16x32_bf16 v[60:63], v[162:165], v[222:225], v[60:63]
	v_mfma_f32_16x16x32_bf16 v[56:59], v[166:169], v[218:221], v[56:59]
	v_mfma_f32_16x16x32_bf16 v[56:59], v[198:201], v[222:225], v[56:59]
	v_mfma_f32_16x16x32_bf16 v[44:47], v[158:161], v[226:229], v[44:47]
	v_mfma_f32_16x16x32_bf16 v[44:47], v[162:165], v[230:233], v[44:47]
	v_mfma_f32_16x16x32_bf16 v[40:43], v[166:169], v[226:229], v[40:43]
	v_mfma_f32_16x16x32_bf16 v[40:43], v[198:201], v[230:233], v[40:43]
	v_mfma_f32_16x16x32_bf16 v[28:31], v[158:161], v[234:237], v[28:31]
	v_mfma_f32_16x16x32_bf16 v[28:31], v[162:165], v[238:241], v[28:31]
	v_mfma_f32_16x16x32_bf16 v[24:27], v[166:169], v[234:237], v[24:27]
	v_mfma_f32_16x16x32_bf16 v[24:27], v[198:201], v[238:241], v[24:27]
	v_mfma_f32_16x16x32_bf16 v[12:15], v[158:161], v[242:245], v[12:15]
	v_mfma_f32_16x16x32_bf16 v[12:15], v[162:165], v[246:249], v[12:15]
	v_mfma_f32_16x16x32_bf16 v[8:11], v[166:169], v[242:245], v[8:11]
	v_mfma_f32_16x16x32_bf16 v[8:11], v[198:201], v[246:249], v[8:11]
	s_setprio 0
	s_setprio 1
	v_mfma_f32_16x16x32_bf16 v[52:55], v[202:205], v[218:221], v[52:55]
	v_mfma_f32_16x16x32_bf16 v[52:55], v[206:209], v[222:225], v[52:55]
	v_mfma_f32_16x16x32_bf16 v[48:51], v[210:213], v[218:221], v[48:51]
	v_mfma_f32_16x16x32_bf16 v[48:51], v[214:217], v[222:225], v[48:51]
	v_mfma_f32_16x16x32_bf16 v[36:39], v[202:205], v[226:229], v[36:39]
	v_mfma_f32_16x16x32_bf16 v[36:39], v[206:209], v[230:233], v[36:39]
	v_mfma_f32_16x16x32_bf16 v[32:35], v[210:213], v[226:229], v[32:35]
	v_mfma_f32_16x16x32_bf16 v[32:35], v[214:217], v[230:233], v[32:35]
	v_mfma_f32_16x16x32_bf16 v[20:23], v[202:205], v[234:237], v[20:23]
	v_mfma_f32_16x16x32_bf16 v[20:23], v[206:209], v[238:241], v[20:23]
	v_mfma_f32_16x16x32_bf16 v[16:19], v[210:213], v[234:237], v[16:19]
	v_mfma_f32_16x16x32_bf16 v[16:19], v[214:217], v[238:241], v[16:19]
	v_mfma_f32_16x16x32_bf16 v[4:7], v[202:205], v[242:245], v[4:7]
	v_mfma_f32_16x16x32_bf16 v[4:7], v[206:209], v[246:249], v[4:7]
	v_mfma_f32_16x16x32_bf16 v[0:3], v[210:213], v[242:245], v[0:3]
	v_mfma_f32_16x16x32_bf16 v[0:3], v[214:217], v[246:249], v[0:3]
	s_setprio 0
	s_barrier
	s_add_i32 s58, s58, 2
	s_add_u32 s55, s55, 0x100000
	s_addc_u32 s57, s57, 0
	s_add_u32 s16, s16, 0x400000
	s_addc_u32 s17, s17, 0
	s_cmp_gt_u32 s58, 29
	s_cbranch_scc0 .LBB0_347
	s_and_b64 vcc, exec, s[68:69]
	s_cbranch_vccz .LBB0_350
	s_barrier

; #define PG8_STAGE(bufoff, gbase, voff) do { _Pragma("unroll") for (int _i = 0; _i < 2; ++_i) \
;         __builtin_amdgcn_global_load_lds((const unsigned*)((const char*)(gbase) + (voff)[_i]), (LAS unsigned*)(lds + (bufoff) + ldsw + _i * 8192), 16, 0, 0); } while (0)
; #define PG8_LDA(dst, b, h) do { _Pragma("unroll") for (int m = 0; m < 4; ++m) _Pragma("unroll") for (int k = 0; k < 2; ++k) dst[m][k] = *(const LAS bf16x8*)(lds + PG8_SA(b, h) + aoff + m * 2048 + k * 1024); } while (0)
; #define PG8_LDB(dst, b, h) do { _Pragma("unroll") for (int n = 0; n < 2; ++n) _Pragma("unroll") for (int k = 0; k < 2; ++k) dst[n][k] = *(const LAS bf16x8*)(lds + PG8_SB(b, h) + boff + n * 2048 + k * 1024); } while (0)
; #define PG8_MMA(ai, bj, At, Bt) do { __builtin_amdgcn_s_setprio(1); _Pragma("unroll") for (int m = 0; m < 4; ++m) _Pragma("unroll") for (int n = 0; n < 2; ++n) _Pragma("unroll") for (int k = 0; k < 2; ++k) \
;         acc[ai][bj][m][n] = __builtin_amdgcn_mfma_f32_16x16x32_bf16(Bt[n][k], At[m][k], acc[ai][bj][m][n], 0, 0, 0); __builtin_amdgcn_s_setprio(0); } while (0)
; #define PG8_WAIT_V(n) asm volatile("s_waitcnt vmcnt(" #n ")" ::: "memory")
; #define PG8_WAIT_L(n) asm volatile("s_waitcnt lgkmcnt(" #n ")" ::: "memory")
; #define PG8_BAR __builtin_amdgcn_s_barrier()
; template <bool ALIGN_EPI, class Epi, class Sched>
; __device__ __forceinline__ void gemm_phase(LAS unsigned char* lds, const int lda, const int ldb, const int K, const Sched& S, const Epi& E, const size_t kstepA = (size_t)(BK * 2), const size_t kstepB = (size_t)(BK * 2)) {
;     ...
;             const bool last = (t == nt - 2);
;             const char* a1 = cA + (size_t)(t + 1) * kstepA;
;             const char* a2 = last ? nA : cA + (size_t)(t + 2) * kstepA; const char* b2 = last ? nB : cB + (size_t)(t + 2) * kstep;
;             const char* a3 = a2 + kstepA; const char* b3 = b2 + kstep;
;             PG8_LDB(B0, 0, 0); PG8_LDB(B1, 0, 1); PG8_SCHED; PG8_LDA(At, 0, 0); PG8_STAGE(PG8_SA(1, 1), a1 + hstepA, voffA);
;             PG8_WAIT_V(8); PG8_WAIT_L(0); PG8_BAR; PG8_MMA(0, 0, At, B0); PG8_MMA(0, 1, At, B1); PG8_BAR; PG8_SCHED;
;             PG8_LDA(At, 0, 1); PG8_STAGE(PG8_SB(0, 0), b2, voffB); PG8_STAGE(PG8_SB(0, 1), b2 + hstepB, voffB); PG8_STAGE(PG8_SA(0, 0), a2, voffA);
;             PG8_WAIT_V(8); PG8_WAIT_L(0); PG8_BAR; PG8_MMA(1, 0, At, B0); PG8_MMA(1, 1, At, B1); PG8_BAR; PG8_SCHED;
.LBB0_726:
	ds_read_b128 v[88:91], v219
	ds_read_b128 v[92:95], v219 offset:1024
	ds_read_b128 v[112:115], v219 offset:2048
	ds_read_b128 v[116:119], v219 offset:3072
	ds_read_b128 v[144:147], v220
	ds_read_b128 v[148:151], v220 offset:1024
	ds_read_b128 v[152:155], v220 offset:2048
	ds_read_b128 v[156:159], v220 offset:3072
	s_add_u32 s14, s12, 0x1fc000
	s_addc_u32 s15, s13, 0
	s_cmp_eq_u32 s67, 28
	s_cselect_b32 s20, s0, s14
	s_cselect_b32 s21, s1, s15
	s_cselect_b32 s16, s6, s22
	s_cselect_b32 s17, s7, s23
	s_add_u32 s14, s20, 0x200000
	s_addc_u32 s15, s21, 0
	s_add_i32 m0, s19, 0xc000
	ds_read_b128 v[160:163], v221
	ds_read_b128 v[164:167], v221 offset:1024
	ds_read_b128 v[188:191], v221 offset:2048
	ds_read_b128 v[192:195], v221 offset:3072
	ds_read_b128 v[196:199], v221 offset:4096
	ds_read_b128 v[200:203], v221 offset:5120
	ds_read_b128 v[204:207], v221 offset:6144
	ds_read_b128 v[208:211], v221 offset:7168
	global_load_lds_dwordx4 v178, s[12:13]
	s_add_i32 m0, s19, 0xe000
	s_nop 0
	global_load_lds_dwordx4 v180, s[12:13]
	s_waitcnt vmcnt(8)
	s_waitcnt lgkmcnt(0)
	s_barrier
	s_setprio 1
	s_waitcnt lgkmcnt(0)
	v_mfma_f32_16x16x32_bf16 v[140:143], v[88:91], v[160:163], v[140:143]
	v_mfma_f32_16x16x32_bf16 v[140:143], v[92:95], v[164:167], v[140:143]
	v_mfma_f32_16x16x32_bf16 v[136:139], v[112:115], v[160:163], v[136:139]
	v_mfma_f32_16x16x32_bf16 v[136:139], v[116:119], v[164:167], v[136:139]
	v_mfma_f32_16x16x32_bf16 v[124:127], v[88:91], v[188:191], v[124:127]
	v_mfma_f32_16x16x32_bf16 v[124:127], v[92:95], v[192:195], v[124:127]
	v_mfma_f32_16x16x32_bf16 v[120:123], v[112:115], v[188:191], v[120:123]
	v_mfma_f32_16x16x32_bf16 v[120:123], v[116:119], v[192:195], v[120:123]
	v_mfma_f32_16x16x32_bf16 v[100:103], v[88:91], v[196:199], v[100:103]
	v_mfma_f32_16x16x32_bf16 v[100:103], v[92:95], v[200:203], v[100:103]
	v_mfma_f32_16x16x32_bf16 v[96:99], v[112:115], v[196:199], v[96:99]
	v_mfma_f32_16x16x32_bf16 v[96:99], v[116:119], v[200:203], v[96:99]
	v_mfma_f32_16x16x32_bf16 v[76:79], v[88:91], v[204:207], v[76:79]
	v_mfma_f32_16x16x32_bf16 v[76:79], v[92:95], v[208:211], v[76:79]
	v_mfma_f32_16x16x32_bf16 v[72:75], v[112:115], v[204:207], v[72:75]
	v_mfma_f32_16x16x32_bf16 v[72:75], v[116:119], v[208:211], v[72:75]
	s_setprio 0
	s_setprio 1
	v_mfma_f32_16x16x32_bf16 v[132:135], v[144:147], v[160:163], v[132:135]
	v_mfma_f32_16x16x32_bf16 v[132:135], v[148:151], v[164:167], v[132:135]
	v_mfma_f32_16x16x32_bf16 v[128:131], v[152:155], v[160:163], v[128:131]
	v_mfma_f32_16x16x32_bf16 v[128:131], v[156:159], v[164:167], v[128:131]
	v_mfma_f32_16x16x32_bf16 v[108:111], v[144:147], v[188:191], v[108:111]
	v_mfma_f32_16x16x32_bf16 v[108:111], v[148:151], v[192:195], v[108:111]
	v_mfma_f32_16x16x32_bf16 v[104:107], v[152:155], v[188:191], v[104:107]
	v_mfma_f32_16x16x32_bf16 v[104:107], v[156:159], v[192:195], v[104:107]
	v_mfma_f32_16x16x32_bf16 v[84:87], v[144:147], v[196:199], v[84:87]
	v_mfma_f32_16x16x32_bf16 v[84:87], v[148:151], v[200:203], v[84:87]
	v_mfma_f32_16x16x32_bf16 v[80:83], v[152:155], v[196:199], v[80:83]
	v_mfma_f32_16x16x32_bf16 v[80:83], v[156:159], v[200:203], v[80:83]
	v_mfma_f32_16x16x32_bf16 v[68:71], v[144:147], v[204:207], v[68:71]
	v_mfma_f32_16x16x32_bf16 v[68:71], v[148:151], v[208:211], v[68:71]
	v_mfma_f32_16x16x32_bf16 v[64:67], v[152:155], v[204:207], v[64:67]
	v_mfma_f32_16x16x32_bf16 v[64:67], v[156:159], v[208:211], v[64:67]
	s_setprio 0
	s_barrier
	s_add_i32 s69, s65, s18
	s_mov_b32 m0, s69
	ds_read_b128 v[160:163], v221 offset:16384
	ds_read_b128 v[164:167], v221 offset:17408
	ds_read_b128 v[188:191], v221 offset:18432
	ds_read_b128 v[192:195], v221 offset:19456
	ds_read_b128 v[196:199], v221 offset:20480
	ds_read_b128 v[200:203], v221 offset:21504
	ds_read_b128 v[204:207], v221 offset:22528
	ds_read_b128 v[208:211], v221 offset:23552
	global_load_lds_dwordx4 v170, s[16:17]
	s_add_i32 m0, s69, 0x2000
	s_add_u32 s78, s16, 0x4000
	s_addc_u32 s79, s17, 0
	s_add_i32 s69, s74, s18
	global_load_lds_dwordx4 v174, s[16:17]
	s_mov_b32 m0, s69
	s_nop 0
	global_load_lds_dwordx4 v170, s[78:79]
	s_add_i32 m0, s69, 0x2000
	s_nop 0
	global_load_lds_dwordx4 v174, s[78:79]
	s_mov_b32 m0, s19
	s_nop 0
	global_load_lds_dwordx4 v168, s[20:21]
	s_mov_b32 m0, s30
	s_nop 0
	global_load_lds_dwordx4 v172, s[20:21]
	s_waitcnt vmcnt(8)
	s_waitcnt lgkmcnt(0)
	s_barrier
	s_setprio 1
	s_waitcnt lgkmcnt(0)
	v_mfma_f32_16x16x32_bf16 v[60:63], v[88:91], v[160:163], v[60:63]
	v_mfma_f32_16x16x32_bf16 v[60:63], v[92:95], v[164:167], v[60:63]
	v_mfma_f32_16x16x32_bf16 v[56:59], v[112:115], v[160:163], v[56:59]
	v_mfma_f32_16x16x32_bf16 v[56:59], v[116:119], v[164:167], v[56:59]
	v_mfma_f32_16x16x32_bf16 v[44:47], v[88:91], v[188:191], v[44:47]
	v_mfma_f32_16x16x32_bf16 v[44:47], v[92:95], v[192:195], v[44:47]
	v_mfma_f32_16x16x32_bf16 v[40:43], v[112:115], v[188:191], v[40:43]
	v_mfma_f32_16x16x32_bf16 v[40:43], v[116:119], v[192:195], v[40:43]
	v_mfma_f32_16x16x32_bf16 v[28:31], v[88:91], v[196:199], v[28:31]
	v_mfma_f32_16x16x32_bf16 v[28:31], v[92:95], v[200:203], v[28:31]
	v_mfma_f32_16x16x32_bf16 v[24:27], v[112:115], v[196:199], v[24:27]
	v_mfma_f32_16x16x32_bf16 v[24:27], v[116:119], v[200:203], v[24:27]
	v_mfma_f32_16x16x32_bf16 v[12:15], v[88:91], v[204:207], v[12:15]
	v_mfma_f32_16x16x32_bf16 v[12:15], v[92:95], v[208:211], v[12:15]
	v_mfma_f32_16x16x32_bf16 v[8:11], v[112:115], v[204:207], v[8:11]
	v_mfma_f32_16x16x32_bf16 v[8:11], v[116:119], v[208:211], v[8:11]
	s_setprio 0
	s_setprio 1
	v_mfma_f32_16x16x32_bf16 v[52:55], v[144:147], v[160:163], v[52:55]
	v_mfma_f32_16x16x32_bf16 v[52:55], v[148:151], v[164:167], v[52:55]
	v_mfma_f32_16x16x32_bf16 v[48:51], v[152:155], v[160:163], v[48:51]
	v_mfma_f32_16x16x32_bf16 v[48:51], v[156:159], v[164:167], v[48:51]
	v_mfma_f32_16x16x32_bf16 v[36:39], v[144:147], v[188:191], v[36:39]
	v_mfma_f32_16x16x32_bf16 v[36:39], v[148:151], v[192:195], v[36:39]
	v_mfma_f32_16x16x32_bf16 v[32:35], v[152:155], v[188:191], v[32:35]
	v_mfma_f32_16x16x32_bf16 v[32:35], v[156:159], v[192:195], v[32:35]
	v_mfma_f32_16x16x32_bf16 v[20:23], v[144:147], v[196:199], v[20:23]
	v_mfma_f32_16x16x32_bf16 v[20:23], v[148:151], v[200:203], v[20:23]
	v_mfma_f32_16x16x32_bf16 v[16:19], v[152:155], v[196:199], v[16:19]
	v_mfma_f32_16x16x32_bf16 v[16:19], v[156:159], v[200:203], v[16:19]
	v_mfma_f32_16x16x32_bf16 v[4:7], v[144:147], v[204:207], v[4:7]
	v_mfma_f32_16x16x32_bf16 v[4:7], v[148:151], v[208:211], v[4:7]
	v_mfma_f32_16x16x32_bf16 v[0:3], v[152:155], v[204:207], v[0:3]
	v_mfma_f32_16x16x32_bf16 v[0:3], v[156:159], v[208:211], v[0:3]
	s_setprio 0
	s_barrier
; #define PG8_STAGE(bufoff, gbase, voff) do { _Pragma("unroll") for (int _i = 0; _i < 2; ++_i) \
;         __builtin_amdgcn_global_load_lds((const unsigned*)((const char*)(gbase) + (voff)[_i]), (LAS unsigned*)(lds + (bufoff) + ldsw + _i * 8192), 16, 0, 0); } while (0)
; #define PG8_LDA(dst, b, h) do { _Pragma("unroll") for (int m = 0; m < 4; ++m) _Pragma("unroll") for (int k = 0; k < 2; ++k) dst[m][k] = *(const LAS bf16x8*)(lds + PG8_SA(b, h) + aoff + m * 2048 + k * 1024); } while (0)
; #define PG8_LDB(dst, b, h) do { _Pragma("unroll") for (int n = 0; n < 2; ++n) _Pragma("unroll") for (int k = 0; k < 2; ++k) dst[n][k] = *(const LAS bf16x8*)(lds + PG8_SB(b, h) + boff + n * 2048 + k * 1024); } while (0)
; #define PG8_MMA(ai, bj, At, Bt) do { __builtin_amdgcn_s_setprio(1); _Pragma("unroll") for (int m = 0; m < 4; ++m) _Pragma("unroll") for (int n = 0; n < 2; ++n) _Pragma("unroll") for (int k = 0; k < 2; ++k) \
;         acc[ai][bj][m][n] = __builtin_amdgcn_mfma_f32_16x16x32_bf16(Bt[n][k], At[m][k], acc[ai][bj][m][n], 0, 0, 0); __builtin_amdgcn_s_setprio(0); } while (0)
; #define PG8_WAIT_V(n) asm volatile("s_waitcnt vmcnt(" #n ")" ::: "memory")
; #define PG8_WAIT_L(n) asm volatile("s_waitcnt lgkmcnt(" #n ")" ::: "memory")
; #define PG8_BAR __builtin_amdgcn_s_barrier()
; #define PG8_SCHED __builtin_amdgcn_sched_barrier(0)
; template <bool ALIGN_EPI, class Epi, class Sched>
; __device__ __forceinline__ void gemm_phase(LAS unsigned char* lds, const int lda, const int ldb, const int K, const Sched& S, const Epi& E, const size_t kstepA = (size_t)(BK * 2), const size_t kstepB = (size_t)(BK * 2)) {
;     ...
;             PG8_LDB(B0, 1, 0); PG8_LDB(B1, 1, 1); PG8_SCHED; PG8_LDA(At, 1, 0); PG8_STAGE(PG8_SA(0, 1), a2 + hstepA, voffA);
;             PG8_WAIT_V(8); PG8_WAIT_L(0); PG8_BAR; PG8_MMA(0, 0, At, B0); PG8_MMA(0, 1, At, B1); PG8_BAR; PG8_SCHED;
;             PG8_LDA(At, 1, 1); PG8_STAGE(PG8_SB(1, 0), b3, voffB); PG8_STAGE(PG8_SB(1, 1), b3 + hstepB, voffB); PG8_STAGE(PG8_SA(1, 0), a3, voffA);
;             PG8_WAIT_V(8); PG8_WAIT_L(0); PG8_BAR; PG8_MMA(1, 0, At, B0); PG8_MMA(1, 1, At, B1); PG8_BAR; PG8_SCHED;
;         }
;         if constexpr (ALIGN_EPI) { if (wr == 0) PG8_BAR; }
	s_add_i32 s69, 0, 0x18000
	s_add_i32 s77, 0, 0x1c000
	v_add_u32_e32 v116, s69, v218
	v_add_u32_e32 v156, s77, v218
	ds_read_b128 v[88:91], v116
	ds_read_b128 v[92:95], v116 offset:1024
	ds_read_b128 v[112:115], v116 offset:2048
	ds_read_b128 v[116:119], v116 offset:3072
	ds_read_b128 v[144:147], v156
	ds_read_b128 v[148:151], v156 offset:1024
	ds_read_b128 v[152:155], v156 offset:2048
	ds_read_b128 v[156:159], v156 offset:3072
	s_add_u32 s20, s20, 0x4000
	s_addc_u32 s21, s21, 0
	s_mov_b32 m0, s33
	ds_read_b128 v[160:163], v221 offset:32768
	ds_read_b128 v[164:167], v221 offset:33792
	ds_read_b128 v[188:191], v221 offset:34816
	ds_read_b128 v[192:195], v221 offset:35840
	ds_read_b128 v[196:199], v221 offset:36864
	ds_read_b128 v[200:203], v221 offset:37888
	ds_read_b128 v[204:207], v221 offset:38912
	ds_read_b128 v[208:211], v221 offset:39936
	global_load_lds_dwordx4 v168, s[20:21]
	s_mov_b32 m0, s42
	s_nop 0
	global_load_lds_dwordx4 v172, s[20:21]
	s_waitcnt vmcnt(8)
	s_waitcnt lgkmcnt(0)
	s_barrier
	s_setprio 1
	s_waitcnt lgkmcnt(0)
	v_mfma_f32_16x16x32_bf16 v[140:143], v[88:91], v[160:163], v[140:143]
	v_mfma_f32_16x16x32_bf16 v[140:143], v[92:95], v[164:167], v[140:143]
	v_mfma_f32_16x16x32_bf16 v[136:139], v[112:115], v[160:163], v[136:139]
	v_mfma_f32_16x16x32_bf16 v[136:139], v[116:119], v[164:167], v[136:139]
	v_mfma_f32_16x16x32_bf16 v[124:127], v[88:91], v[188:191], v[124:127]
	v_mfma_f32_16x16x32_bf16 v[124:127], v[92:95], v[192:195], v[124:127]
	v_mfma_f32_16x16x32_bf16 v[120:123], v[112:115], v[188:191], v[120:123]
	v_mfma_f32_16x16x32_bf16 v[120:123], v[116:119], v[192:195], v[120:123]
	v_mfma_f32_16x16x32_bf16 v[100:103], v[88:91], v[196:199], v[100:103]
	v_mfma_f32_16x16x32_bf16 v[100:103], v[92:95], v[200:203], v[100:103]
	v_mfma_f32_16x16x32_bf16 v[96:99], v[112:115], v[196:199], v[96:99]
	v_mfma_f32_16x16x32_bf16 v[96:99], v[116:119], v[200:203], v[96:99]
	v_mfma_f32_16x16x32_bf16 v[76:79], v[88:91], v[204:207], v[76:79]
	v_mfma_f32_16x16x32_bf16 v[76:79], v[92:95], v[208:211], v[76:79]
	v_mfma_f32_16x16x32_bf16 v[72:75], v[112:115], v[204:207], v[72:75]
	v_mfma_f32_16x16x32_bf16 v[72:75], v[116:119], v[208:211], v[72:75]
	s_setprio 0
	s_setprio 1
	v_mfma_f32_16x16x32_bf16 v[132:135], v[144:147], v[160:163], v[132:135]
	v_mfma_f32_16x16x32_bf16 v[132:135], v[148:151], v[164:167], v[132:135]
	v_mfma_f32_16x16x32_bf16 v[128:131], v[152:155], v[160:163], v[128:131]
	v_mfma_f32_16x16x32_bf16 v[128:131], v[156:159], v[164:167], v[128:131]
	v_mfma_f32_16x16x32_bf16 v[108:111], v[144:147], v[188:191], v[108:111]
	v_mfma_f32_16x16x32_bf16 v[108:111], v[148:151], v[192:195], v[108:111]
	v_mfma_f32_16x16x32_bf16 v[104:107], v[152:155], v[188:191], v[104:107]
	v_mfma_f32_16x16x32_bf16 v[104:107], v[156:159], v[192:195], v[104:107]
	v_mfma_f32_16x16x32_bf16 v[84:87], v[144:147], v[196:199], v[84:87]
	v_mfma_f32_16x16x32_bf16 v[84:87], v[148:151], v[200:203], v[84:87]
	v_mfma_f32_16x16x32_bf16 v[80:83], v[152:155], v[196:199], v[80:83]
	v_mfma_f32_16x16x32_bf16 v[80:83], v[156:159], v[200:203], v[80:83]
	v_mfma_f32_16x16x32_bf16 v[68:71], v[144:147], v[204:207], v[68:71]
	v_mfma_f32_16x16x32_bf16 v[68:71], v[148:151], v[208:211], v[68:71]
	v_mfma_f32_16x16x32_bf16 v[64:67], v[152:155], v[204:207], v[64:67]
	v_mfma_f32_16x16x32_bf16 v[64:67], v[156:159], v[208:211], v[64:67]
	s_setprio 0
	s_barrier
	s_add_u32 s20, s16, 0x40000
	s_addc_u32 s21, s17, 0
	s_add_i32 s69, s69, s18
	s_mov_b32 m0, s69
	ds_read_b128 v[160:163], v221 offset:49152
	ds_read_b128 v[164:167], v221 offset:50176
	ds_read_b128 v[188:191], v221 offset:51200
	ds_read_b128 v[192:195], v221 offset:52224
	ds_read_b128 v[196:199], v221 offset:53248
	ds_read_b128 v[200:203], v221 offset:54272
	ds_read_b128 v[204:207], v221 offset:55296
	ds_read_b128 v[208:211], v221 offset:56320
	global_load_lds_dwordx4 v170, s[20:21]
	s_add_i32 m0, s69, 0x2000
	s_add_u32 s16, s16, 0x44000
	global_load_lds_dwordx4 v174, s[20:21]
	s_addc_u32 s17, s17, 0
	s_add_i32 s20, s77, s18
	s_mov_b32 m0, s20
	s_nop 0
	global_load_lds_dwordx4 v170, s[16:17]
	s_add_i32 m0, s20, 0x2000
	s_nop 0
	global_load_lds_dwordx4 v174, s[16:17]
	s_mov_b32 m0, s51
	s_nop 0
	global_load_lds_dwordx4 v168, s[14:15]
	s_mov_b32 m0, s64
	s_nop 0
	global_load_lds_dwordx4 v172, s[14:15]
	s_waitcnt vmcnt(8)
	s_waitcnt lgkmcnt(0)
	s_barrier
	s_setprio 1
	s_waitcnt lgkmcnt(0)
	v_mfma_f32_16x16x32_bf16 v[60:63], v[88:91], v[160:163], v[60:63]
	v_mfma_f32_16x16x32_bf16 v[60:63], v[92:95], v[164:167], v[60:63]
	v_mfma_f32_16x16x32_bf16 v[56:59], v[112:115], v[160:163], v[56:59]
	v_mfma_f32_16x16x32_bf16 v[56:59], v[116:119], v[164:167], v[56:59]
	v_mfma_f32_16x16x32_bf16 v[44:47], v[88:91], v[188:191], v[44:47]
	v_mfma_f32_16x16x32_bf16 v[44:47], v[92:95], v[192:195], v[44:47]
	v_mfma_f32_16x16x32_bf16 v[40:43], v[112:115], v[188:191], v[40:43]
	v_mfma_f32_16x16x32_bf16 v[40:43], v[116:119], v[192:195], v[40:43]
	v_mfma_f32_16x16x32_bf16 v[28:31], v[88:91], v[196:199], v[28:31]
	v_mfma_f32_16x16x32_bf16 v[28:31], v[92:95], v[200:203], v[28:31]
	v_mfma_f32_16x16x32_bf16 v[24:27], v[112:115], v[196:199], v[24:27]
	v_mfma_f32_16x16x32_bf16 v[24:27], v[116:119], v[200:203], v[24:27]
	v_mfma_f32_16x16x32_bf16 v[12:15], v[88:91], v[204:207], v[12:15]
	v_mfma_f32_16x16x32_bf16 v[12:15], v[92:95], v[208:211], v[12:15]
	v_mfma_f32_16x16x32_bf16 v[8:11], v[112:115], v[204:207], v[8:11]
	v_mfma_f32_16x16x32_bf16 v[8:11], v[116:119], v[208:211], v[8:11]
	s_setprio 0
	s_setprio 1
	v_mfma_f32_16x16x32_bf16 v[52:55], v[144:147], v[160:163], v[52:55]
	v_mfma_f32_16x16x32_bf16 v[52:55], v[148:151], v[164:167], v[52:55]
	v_mfma_f32_16x16x32_bf16 v[48:51], v[152:155], v[160:163], v[48:51]
	v_mfma_f32_16x16x32_bf16 v[48:51], v[156:159], v[164:167], v[48:51]
	v_mfma_f32_16x16x32_bf16 v[36:39], v[144:147], v[188:191], v[36:39]
	v_mfma_f32_16x16x32_bf16 v[36:39], v[148:151], v[192:195], v[36:39]
	v_mfma_f32_16x16x32_bf16 v[32:35], v[152:155], v[188:191], v[32:35]
	v_mfma_f32_16x16x32_bf16 v[32:35], v[156:159], v[192:195], v[32:35]
	v_mfma_f32_16x16x32_bf16 v[20:23], v[144:147], v[196:199], v[20:23]
	v_mfma_f32_16x16x32_bf16 v[20:23], v[148:151], v[200:203], v[20:23]
	v_mfma_f32_16x16x32_bf16 v[16:19], v[152:155], v[196:199], v[16:19]
	v_mfma_f32_16x16x32_bf16 v[16:19], v[156:159], v[200:203], v[16:19]
	v_mfma_f32_16x16x32_bf16 v[4:7], v[144:147], v[204:207], v[4:7]
	v_mfma_f32_16x16x32_bf16 v[4:7], v[148:151], v[208:211], v[4:7]
	v_mfma_f32_16x16x32_bf16 v[0:3], v[152:155], v[204:207], v[0:3]
	v_mfma_f32_16x16x32_bf16 v[0:3], v[156:159], v[208:211], v[0:3]
	s_setprio 0
	s_barrier
	s_add_i32 s67, s67, 2
	s_add_u32 s22, s22, 0x80000
	s_addc_u32 s23, s23, 0
	s_add_u32 s12, s12, 0x400000
	s_addc_u32 s13, s13, 0
	s_cmp_gt_u32 s67, 29
	s_cbranch_scc0 .LBB0_726
	s_and_b64 vcc, exec, s[56:57]
	s_cbranch_vccz .LBB0_729
	s_barrier

; #define PG8_STAGE(bufoff, gbase, voff) do { _Pragma("unroll") for (int _i = 0; _i < 2; ++_i) \
;         __builtin_amdgcn_global_load_lds((const unsigned*)((const char*)(gbase) + (voff)[_i]), (LAS unsigned*)(lds + (bufoff) + ldsw + _i * 8192), 16, 0, 0); } while (0)
; #define PG8_LDA(dst, b, h) do { _Pragma("unroll") for (int m = 0; m < 4; ++m) _Pragma("unroll") for (int k = 0; k < 2; ++k) dst[m][k] = *(const LAS bf16x8*)(lds + PG8_SA(b, h) + aoff + m * 2048 + k * 1024); } while (0)
; #define PG8_LDB(dst, b, h) do { _Pragma("unroll") for (int n = 0; n < 2; ++n) _Pragma("unroll") for (int k = 0; k < 2; ++k) dst[n][k] = *(const LAS bf16x8*)(lds + PG8_SB(b, h) + boff + n * 2048 + k * 1024); } while (0)
; #define PG8_MMA(ai, bj, At, Bt) do { __builtin_amdgcn_s_setprio(1); _Pragma("unroll") for (int m = 0; m < 4; ++m) _Pragma("unroll") for (int n = 0; n < 2; ++n) _Pragma("unroll") for (int k = 0; k < 2; ++k) \
;         acc[ai][bj][m][n] = __builtin_amdgcn_mfma_f32_16x16x32_bf16(Bt[n][k], At[m][k], acc[ai][bj][m][n], 0, 0, 0); __builtin_amdgcn_s_setprio(0); } while (0)
; #define PG8_WAIT_V(n) asm volatile("s_waitcnt vmcnt(" #n ")" ::: "memory")
; #define PG8_WAIT_L(n) asm volatile("s_waitcnt lgkmcnt(" #n ")" ::: "memory")
; #define PG8_BAR __builtin_amdgcn_s_barrier()
; template <bool ALIGN_EPI, class Epi, class Sched>
; __device__ __forceinline__ void gemm_phase(LAS unsigned char* lds, const int lda, const int ldb, const int K, const Sched& S, const Epi& E, const size_t kstepA = (size_t)(BK * 2), const size_t kstepB = (size_t)(BK * 2)) {
;     ...
;             const bool last = (t == nt - 2);
;             const char* a1 = cA + (size_t)(t + 1) * kstepA;
;             const char* a2 = last ? nA : cA + (size_t)(t + 2) * kstepA; const char* b2 = last ? nB : cB + (size_t)(t + 2) * kstep;
;             const char* a3 = a2 + kstepA; const char* b3 = b2 + kstep;
;             PG8_LDB(B0, 0, 0); PG8_LDB(B1, 0, 1); PG8_SCHED; PG8_LDA(At, 0, 0); PG8_STAGE(PG8_SA(1, 1), a1 + hstepA, voffA);
;             PG8_WAIT_V(8); PG8_WAIT_L(0); PG8_BAR; PG8_MMA(0, 0, At, B0); PG8_MMA(0, 1, At, B1); PG8_BAR; PG8_SCHED;
;             PG8_LDA(At, 0, 1); PG8_STAGE(PG8_SB(0, 0), b2, voffB); PG8_STAGE(PG8_SB(0, 1), b2 + hstepB, voffB); PG8_STAGE(PG8_SA(0, 0), a2, voffA);
;             PG8_WAIT_V(8); PG8_WAIT_L(0); PG8_BAR; PG8_MMA(1, 0, At, B0); PG8_MMA(1, 1, At, B1); PG8_BAR; PG8_SCHED;
.LBB0_952:
	ds_read_b128 v[88:91], v219
	ds_read_b128 v[92:95], v219 offset:1024
	ds_read_b128 v[112:115], v219 offset:2048
	ds_read_b128 v[116:119], v219 offset:3072
	ds_read_b128 v[144:147], v220
	ds_read_b128 v[148:151], v220 offset:1024
	ds_read_b128 v[152:155], v220 offset:2048
	ds_read_b128 v[156:159], v220 offset:3072
	s_add_u32 s14, s12, 0x1fc000
	s_addc_u32 s15, s13, 0
	s_cmp_eq_u32 s61, 12
	s_cselect_b32 s20, s0, s14
	s_cselect_b32 s21, s1, s15
	s_cselect_b32 s16, s6, s22
	s_cselect_b32 s17, s7, s23
	s_add_u32 s14, s20, 0x200000
	s_addc_u32 s15, s21, 0
	s_add_i32 m0, s19, 0xc000
	ds_read_b128 v[160:163], v221
	ds_read_b128 v[164:167], v221 offset:1024
	ds_read_b128 v[188:191], v221 offset:2048
	ds_read_b128 v[192:195], v221 offset:3072
	ds_read_b128 v[196:199], v221 offset:4096
	ds_read_b128 v[200:203], v221 offset:5120
	ds_read_b128 v[204:207], v221 offset:6144
	ds_read_b128 v[208:211], v221 offset:7168
	global_load_lds_dwordx4 v178, s[12:13]
	s_add_i32 m0, s19, 0xe000
	s_nop 0
	global_load_lds_dwordx4 v180, s[12:13]
	s_waitcnt vmcnt(8)
	s_waitcnt lgkmcnt(0)
	s_barrier
	s_setprio 1
	s_waitcnt lgkmcnt(0)
	v_mfma_f32_16x16x32_bf16 v[140:143], v[88:91], v[160:163], v[140:143]
	v_mfma_f32_16x16x32_bf16 v[140:143], v[92:95], v[164:167], v[140:143]
	v_mfma_f32_16x16x32_bf16 v[136:139], v[112:115], v[160:163], v[136:139]
	v_mfma_f32_16x16x32_bf16 v[136:139], v[116:119], v[164:167], v[136:139]
	v_mfma_f32_16x16x32_bf16 v[124:127], v[88:91], v[188:191], v[124:127]
	v_mfma_f32_16x16x32_bf16 v[124:127], v[92:95], v[192:195], v[124:127]
	v_mfma_f32_16x16x32_bf16 v[120:123], v[112:115], v[188:191], v[120:123]
	v_mfma_f32_16x16x32_bf16 v[120:123], v[116:119], v[192:195], v[120:123]
	v_mfma_f32_16x16x32_bf16 v[100:103], v[88:91], v[196:199], v[100:103]
	v_mfma_f32_16x16x32_bf16 v[100:103], v[92:95], v[200:203], v[100:103]
	v_mfma_f32_16x16x32_bf16 v[96:99], v[112:115], v[196:199], v[96:99]
	v_mfma_f32_16x16x32_bf16 v[96:99], v[116:119], v[200:203], v[96:99]
	v_mfma_f32_16x16x32_bf16 v[76:79], v[88:91], v[204:207], v[76:79]
	v_mfma_f32_16x16x32_bf16 v[76:79], v[92:95], v[208:211], v[76:79]
	v_mfma_f32_16x16x32_bf16 v[72:75], v[112:115], v[204:207], v[72:75]
	v_mfma_f32_16x16x32_bf16 v[72:75], v[116:119], v[208:211], v[72:75]
	s_setprio 0
	s_setprio 1
	v_mfma_f32_16x16x32_bf16 v[132:135], v[144:147], v[160:163], v[132:135]
	v_mfma_f32_16x16x32_bf16 v[132:135], v[148:151], v[164:167], v[132:135]
	v_mfma_f32_16x16x32_bf16 v[128:131], v[152:155], v[160:163], v[128:131]
	v_mfma_f32_16x16x32_bf16 v[128:131], v[156:159], v[164:167], v[128:131]
	v_mfma_f32_16x16x32_bf16 v[108:111], v[144:147], v[188:191], v[108:111]
	v_mfma_f32_16x16x32_bf16 v[108:111], v[148:151], v[192:195], v[108:111]
	v_mfma_f32_16x16x32_bf16 v[104:107], v[152:155], v[188:191], v[104:107]
	v_mfma_f32_16x16x32_bf16 v[104:107], v[156:159], v[192:195], v[104:107]
	v_mfma_f32_16x16x32_bf16 v[84:87], v[144:147], v[196:199], v[84:87]
	v_mfma_f32_16x16x32_bf16 v[84:87], v[148:151], v[200:203], v[84:87]
	v_mfma_f32_16x16x32_bf16 v[80:83], v[152:155], v[196:199], v[80:83]
	v_mfma_f32_16x16x32_bf16 v[80:83], v[156:159], v[200:203], v[80:83]
	v_mfma_f32_16x16x32_bf16 v[68:71], v[144:147], v[204:207], v[68:71]
	v_mfma_f32_16x16x32_bf16 v[68:71], v[148:151], v[208:211], v[68:71]
	v_mfma_f32_16x16x32_bf16 v[64:67], v[152:155], v[204:207], v[64:67]
	v_mfma_f32_16x16x32_bf16 v[64:67], v[156:159], v[208:211], v[64:67]
	s_setprio 0
	s_barrier
	s_add_i32 s63, s71, s18
	s_mov_b32 m0, s63
	ds_read_b128 v[160:163], v221 offset:16384
	ds_read_b128 v[164:167], v221 offset:17408
	ds_read_b128 v[188:191], v221 offset:18432
	ds_read_b128 v[192:195], v221 offset:19456
	ds_read_b128 v[196:199], v221 offset:20480
	ds_read_b128 v[200:203], v221 offset:21504
	ds_read_b128 v[204:207], v221 offset:22528
	ds_read_b128 v[208:211], v221 offset:23552
	global_load_lds_dwordx4 v170, s[16:17]
	s_add_i32 m0, s63, 0x2000
	s_add_u32 s76, s16, 0x4000
	s_addc_u32 s77, s17, 0
	s_add_i32 s63, s72, s18
	global_load_lds_dwordx4 v174, s[16:17]
	s_mov_b32 m0, s63
	s_nop 0
	global_load_lds_dwordx4 v170, s[76:77]
	s_add_i32 m0, s63, 0x2000
	s_nop 0
	global_load_lds_dwordx4 v174, s[76:77]
	s_mov_b32 m0, s19
	s_nop 0
	global_load_lds_dwordx4 v168, s[20:21]
	s_mov_b32 m0, s33
	s_nop 0
	global_load_lds_dwordx4 v172, s[20:21]
	s_waitcnt vmcnt(8)
	s_waitcnt lgkmcnt(0)
	s_barrier
	s_setprio 1
	s_waitcnt lgkmcnt(0)
	v_mfma_f32_16x16x32_bf16 v[60:63], v[88:91], v[160:163], v[60:63]
	v_mfma_f32_16x16x32_bf16 v[60:63], v[92:95], v[164:167], v[60:63]
	v_mfma_f32_16x16x32_bf16 v[56:59], v[112:115], v[160:163], v[56:59]
	v_mfma_f32_16x16x32_bf16 v[56:59], v[116:119], v[164:167], v[56:59]
	v_mfma_f32_16x16x32_bf16 v[44:47], v[88:91], v[188:191], v[44:47]
	v_mfma_f32_16x16x32_bf16 v[44:47], v[92:95], v[192:195], v[44:47]
	v_mfma_f32_16x16x32_bf16 v[40:43], v[112:115], v[188:191], v[40:43]
	v_mfma_f32_16x16x32_bf16 v[40:43], v[116:119], v[192:195], v[40:43]
	v_mfma_f32_16x16x32_bf16 v[28:31], v[88:91], v[196:199], v[28:31]
	v_mfma_f32_16x16x32_bf16 v[28:31], v[92:95], v[200:203], v[28:31]
	v_mfma_f32_16x16x32_bf16 v[24:27], v[112:115], v[196:199], v[24:27]
	v_mfma_f32_16x16x32_bf16 v[24:27], v[116:119], v[200:203], v[24:27]
	v_mfma_f32_16x16x32_bf16 v[12:15], v[88:91], v[204:207], v[12:15]
	v_mfma_f32_16x16x32_bf16 v[12:15], v[92:95], v[208:211], v[12:15]
	v_mfma_f32_16x16x32_bf16 v[8:11], v[112:115], v[204:207], v[8:11]
	v_mfma_f32_16x16x32_bf16 v[8:11], v[116:119], v[208:211], v[8:11]
	s_setprio 0
	s_setprio 1
	v_mfma_f32_16x16x32_bf16 v[52:55], v[144:147], v[160:163], v[52:55]
	v_mfma_f32_16x16x32_bf16 v[52:55], v[148:151], v[164:167], v[52:55]
	v_mfma_f32_16x16x32_bf16 v[48:51], v[152:155], v[160:163], v[48:51]
	v_mfma_f32_16x16x32_bf16 v[48:51], v[156:159], v[164:167], v[48:51]
	v_mfma_f32_16x16x32_bf16 v[36:39], v[144:147], v[188:191], v[36:39]
	v_mfma_f32_16x16x32_bf16 v[36:39], v[148:151], v[192:195], v[36:39]
	v_mfma_f32_16x16x32_bf16 v[32:35], v[152:155], v[188:191], v[32:35]
	v_mfma_f32_16x16x32_bf16 v[32:35], v[156:159], v[192:195], v[32:35]
	v_mfma_f32_16x16x32_bf16 v[20:23], v[144:147], v[196:199], v[20:23]
	v_mfma_f32_16x16x32_bf16 v[20:23], v[148:151], v[200:203], v[20:23]
	v_mfma_f32_16x16x32_bf16 v[16:19], v[152:155], v[196:199], v[16:19]
	v_mfma_f32_16x16x32_bf16 v[16:19], v[156:159], v[200:203], v[16:19]
	v_mfma_f32_16x16x32_bf16 v[4:7], v[144:147], v[204:207], v[4:7]
	v_mfma_f32_16x16x32_bf16 v[4:7], v[148:151], v[208:211], v[4:7]
	v_mfma_f32_16x16x32_bf16 v[0:3], v[152:155], v[204:207], v[0:3]
	v_mfma_f32_16x16x32_bf16 v[0:3], v[156:159], v[208:211], v[0:3]
	s_setprio 0
	s_barrier
; #define PG8_STAGE(bufoff, gbase, voff) do { _Pragma("unroll") for (int _i = 0; _i < 2; ++_i) \
;         __builtin_amdgcn_global_load_lds((const unsigned*)((const char*)(gbase) + (voff)[_i]), (LAS unsigned*)(lds + (bufoff) + ldsw + _i * 8192), 16, 0, 0); } while (0)
; #define PG8_LDA(dst, b, h) do { _Pragma("unroll") for (int m = 0; m < 4; ++m) _Pragma("unroll") for (int k = 0; k < 2; ++k) dst[m][k] = *(const LAS bf16x8*)(lds + PG8_SA(b, h) + aoff + m * 2048 + k * 1024); } while (0)
; #define PG8_LDB(dst, b, h) do { _Pragma("unroll") for (int n = 0; n < 2; ++n) _Pragma("unroll") for (int k = 0; k < 2; ++k) dst[n][k] = *(const LAS bf16x8*)(lds + PG8_SB(b, h) + boff + n * 2048 + k * 1024); } while (0)
; #define PG8_MMA(ai, bj, At, Bt) do { __builtin_amdgcn_s_setprio(1); _Pragma("unroll") for (int m = 0; m < 4; ++m) _Pragma("unroll") for (int n = 0; n < 2; ++n) _Pragma("unroll") for (int k = 0; k < 2; ++k) \
;         acc[ai][bj][m][n] = __builtin_amdgcn_mfma_f32_16x16x32_bf16(Bt[n][k], At[m][k], acc[ai][bj][m][n], 0, 0, 0); __builtin_amdgcn_s_setprio(0); } while (0)
; #define PG8_WAIT_V(n) asm volatile("s_waitcnt vmcnt(" #n ")" ::: "memory")
; #define PG8_WAIT_L(n) asm volatile("s_waitcnt lgkmcnt(" #n ")" ::: "memory")
; #define PG8_BAR __builtin_amdgcn_s_barrier()
; #define PG8_SCHED __builtin_amdgcn_sched_barrier(0)
; template <bool ALIGN_EPI, class Epi, class Sched>
; __device__ __forceinline__ void gemm_phase(LAS unsigned char* lds, const int lda, const int ldb, const int K, const Sched& S, const Epi& E, const size_t kstepA = (size_t)(BK * 2), const size_t kstepB = (size_t)(BK * 2)) {
;     ...
;             PG8_LDB(B0, 1, 0); PG8_LDB(B1, 1, 1); PG8_SCHED; PG8_LDA(At, 1, 0); PG8_STAGE(PG8_SA(0, 1), a2 + hstepA, voffA);
;             PG8_WAIT_V(8); PG8_WAIT_L(0); PG8_BAR; PG8_MMA(0, 0, At, B0); PG8_MMA(0, 1, At, B1); PG8_BAR; PG8_SCHED;
;             PG8_LDA(At, 1, 1); PG8_STAGE(PG8_SB(1, 0), b3, voffB); PG8_STAGE(PG8_SB(1, 1), b3 + hstepB, voffB); PG8_STAGE(PG8_SA(1, 0), a3, voffA);
;             PG8_WAIT_V(8); PG8_WAIT_L(0); PG8_BAR; PG8_MMA(1, 0, At, B0); PG8_MMA(1, 1, At, B1); PG8_BAR; PG8_SCHED;
;         }
;         if constexpr (ALIGN_EPI) { if (wr == 0) PG8_BAR; }
	s_add_i32 s63, 0, 0x18000
	s_add_i32 s75, 0, 0x1c000
	v_add_u32_e32 v116, s63, v218
	v_add_u32_e32 v156, s75, v218
	ds_read_b128 v[88:91], v116
	ds_read_b128 v[92:95], v116 offset:1024
	ds_read_b128 v[112:115], v116 offset:2048
	ds_read_b128 v[116:119], v116 offset:3072
	ds_read_b128 v[144:147], v156
	ds_read_b128 v[148:151], v156 offset:1024
	ds_read_b128 v[152:155], v156 offset:2048
	ds_read_b128 v[156:159], v156 offset:3072
	s_add_u32 s20, s20, 0x4000
	s_addc_u32 s21, s21, 0
	s_mov_b32 m0, s42
	ds_read_b128 v[160:163], v221 offset:32768
	ds_read_b128 v[164:167], v221 offset:33792
	ds_read_b128 v[188:191], v221 offset:34816
	ds_read_b128 v[192:195], v221 offset:35840
	ds_read_b128 v[196:199], v221 offset:36864
	ds_read_b128 v[200:203], v221 offset:37888
	ds_read_b128 v[204:207], v221 offset:38912
	ds_read_b128 v[208:211], v221 offset:39936
	global_load_lds_dwordx4 v168, s[20:21]
	s_mov_b32 m0, s43
	s_nop 0
	global_load_lds_dwordx4 v172, s[20:21]
	s_waitcnt vmcnt(8)
	s_waitcnt lgkmcnt(0)
	s_barrier
	s_setprio 1
	s_waitcnt lgkmcnt(0)
	v_mfma_f32_16x16x32_bf16 v[140:143], v[88:91], v[160:163], v[140:143]
	v_mfma_f32_16x16x32_bf16 v[140:143], v[92:95], v[164:167], v[140:143]
	v_mfma_f32_16x16x32_bf16 v[136:139], v[112:115], v[160:163], v[136:139]
	v_mfma_f32_16x16x32_bf16 v[136:139], v[116:119], v[164:167], v[136:139]
	v_mfma_f32_16x16x32_bf16 v[124:127], v[88:91], v[188:191], v[124:127]
	v_mfma_f32_16x16x32_bf16 v[124:127], v[92:95], v[192:195], v[124:127]
	v_mfma_f32_16x16x32_bf16 v[120:123], v[112:115], v[188:191], v[120:123]
	v_mfma_f32_16x16x32_bf16 v[120:123], v[116:119], v[192:195], v[120:123]
	v_mfma_f32_16x16x32_bf16 v[100:103], v[88:91], v[196:199], v[100:103]
	v_mfma_f32_16x16x32_bf16 v[100:103], v[92:95], v[200:203], v[100:103]
	v_mfma_f32_16x16x32_bf16 v[96:99], v[112:115], v[196:199], v[96:99]
	v_mfma_f32_16x16x32_bf16 v[96:99], v[116:119], v[200:203], v[96:99]
	v_mfma_f32_16x16x32_bf16 v[76:79], v[88:91], v[204:207], v[76:79]
	v_mfma_f32_16x16x32_bf16 v[76:79], v[92:95], v[208:211], v[76:79]
	v_mfma_f32_16x16x32_bf16 v[72:75], v[112:115], v[204:207], v[72:75]
	v_mfma_f32_16x16x32_bf16 v[72:75], v[116:119], v[208:211], v[72:75]
	s_setprio 0
	s_setprio 1
	v_mfma_f32_16x16x32_bf16 v[132:135], v[144:147], v[160:163], v[132:135]
	v_mfma_f32_16x16x32_bf16 v[132:135], v[148:151], v[164:167], v[132:135]
	v_mfma_f32_16x16x32_bf16 v[128:131], v[152:155], v[160:163], v[128:131]
	v_mfma_f32_16x16x32_bf16 v[128:131], v[156:159], v[164:167], v[128:131]
	v_mfma_f32_16x16x32_bf16 v[108:111], v[144:147], v[188:191], v[108:111]
	v_mfma_f32_16x16x32_bf16 v[108:111], v[148:151], v[192:195], v[108:111]
	v_mfma_f32_16x16x32_bf16 v[104:107], v[152:155], v[188:191], v[104:107]
	v_mfma_f32_16x16x32_bf16 v[104:107], v[156:159], v[192:195], v[104:107]
	v_mfma_f32_16x16x32_bf16 v[84:87], v[144:147], v[196:199], v[84:87]
	v_mfma_f32_16x16x32_bf16 v[84:87], v[148:151], v[200:203], v[84:87]
	v_mfma_f32_16x16x32_bf16 v[80:83], v[152:155], v[196:199], v[80:83]
	v_mfma_f32_16x16x32_bf16 v[80:83], v[156:159], v[200:203], v[80:83]
	v_mfma_f32_16x16x32_bf16 v[68:71], v[144:147], v[204:207], v[68:71]
	v_mfma_f32_16x16x32_bf16 v[68:71], v[148:151], v[208:211], v[68:71]
	v_mfma_f32_16x16x32_bf16 v[64:67], v[152:155], v[204:207], v[64:67]
	v_mfma_f32_16x16x32_bf16 v[64:67], v[156:159], v[208:211], v[64:67]
	s_setprio 0
	s_barrier
	s_add_u32 s20, s16, 0x40000
	s_addc_u32 s21, s17, 0
	s_add_i32 s63, s63, s18
	s_mov_b32 m0, s63
	ds_read_b128 v[160:163], v221 offset:49152
	ds_read_b128 v[164:167], v221 offset:50176
	ds_read_b128 v[188:191], v221 offset:51200
	ds_read_b128 v[192:195], v221 offset:52224
	ds_read_b128 v[196:199], v221 offset:53248
	ds_read_b128 v[200:203], v221 offset:54272
	ds_read_b128 v[204:207], v221 offset:55296
	ds_read_b128 v[208:211], v221 offset:56320
	global_load_lds_dwordx4 v170, s[20:21]
	s_add_i32 m0, s63, 0x2000
	s_add_u32 s16, s16, 0x44000
	global_load_lds_dwordx4 v174, s[20:21]
	s_addc_u32 s17, s17, 0
	s_add_i32 s20, s75, s18
	s_mov_b32 m0, s20
	s_nop 0
	global_load_lds_dwordx4 v170, s[16:17]
	s_add_i32 m0, s20, 0x2000
	s_nop 0
	global_load_lds_dwordx4 v174, s[16:17]
	s_mov_b32 m0, s64
	s_nop 0
	global_load_lds_dwordx4 v168, s[14:15]
	s_mov_b32 m0, s65
	s_nop 0
	global_load_lds_dwordx4 v172, s[14:15]
	s_waitcnt vmcnt(8)
	s_waitcnt lgkmcnt(0)
	s_barrier
	s_setprio 1
	s_waitcnt lgkmcnt(0)
	v_mfma_f32_16x16x32_bf16 v[60:63], v[88:91], v[160:163], v[60:63]
	v_mfma_f32_16x16x32_bf16 v[60:63], v[92:95], v[164:167], v[60:63]
	v_mfma_f32_16x16x32_bf16 v[56:59], v[112:115], v[160:163], v[56:59]
	v_mfma_f32_16x16x32_bf16 v[56:59], v[116:119], v[164:167], v[56:59]
	v_mfma_f32_16x16x32_bf16 v[44:47], v[88:91], v[188:191], v[44:47]
	v_mfma_f32_16x16x32_bf16 v[44:47], v[92:95], v[192:195], v[44:47]
	v_mfma_f32_16x16x32_bf16 v[40:43], v[112:115], v[188:191], v[40:43]
	v_mfma_f32_16x16x32_bf16 v[40:43], v[116:119], v[192:195], v[40:43]
	v_mfma_f32_16x16x32_bf16 v[28:31], v[88:91], v[196:199], v[28:31]
	v_mfma_f32_16x16x32_bf16 v[28:31], v[92:95], v[200:203], v[28:31]
	v_mfma_f32_16x16x32_bf16 v[24:27], v[112:115], v[196:199], v[24:27]
	v_mfma_f32_16x16x32_bf16 v[24:27], v[116:119], v[200:203], v[24:27]
	v_mfma_f32_16x16x32_bf16 v[12:15], v[88:91], v[204:207], v[12:15]
	v_mfma_f32_16x16x32_bf16 v[12:15], v[92:95], v[208:211], v[12:15]
	v_mfma_f32_16x16x32_bf16 v[8:11], v[112:115], v[204:207], v[8:11]
	v_mfma_f32_16x16x32_bf16 v[8:11], v[116:119], v[208:211], v[8:11]
	s_setprio 0
	s_setprio 1
	v_mfma_f32_16x16x32_bf16 v[52:55], v[144:147], v[160:163], v[52:55]
	v_mfma_f32_16x16x32_bf16 v[52:55], v[148:151], v[164:167], v[52:55]
	v_mfma_f32_16x16x32_bf16 v[48:51], v[152:155], v[160:163], v[48:51]
	v_mfma_f32_16x16x32_bf16 v[48:51], v[156:159], v[164:167], v[48:51]
	v_mfma_f32_16x16x32_bf16 v[36:39], v[144:147], v[188:191], v[36:39]
	v_mfma_f32_16x16x32_bf16 v[36:39], v[148:151], v[192:195], v[36:39]
	v_mfma_f32_16x16x32_bf16 v[32:35], v[152:155], v[188:191], v[32:35]
	v_mfma_f32_16x16x32_bf16 v[32:35], v[156:159], v[192:195], v[32:35]
	v_mfma_f32_16x16x32_bf16 v[20:23], v[144:147], v[196:199], v[20:23]
	v_mfma_f32_16x16x32_bf16 v[20:23], v[148:151], v[200:203], v[20:23]
	v_mfma_f32_16x16x32_bf16 v[16:19], v[152:155], v[196:199], v[16:19]
	v_mfma_f32_16x16x32_bf16 v[16:19], v[156:159], v[200:203], v[16:19]
	v_mfma_f32_16x16x32_bf16 v[4:7], v[144:147], v[204:207], v[4:7]
	v_mfma_f32_16x16x32_bf16 v[4:7], v[148:151], v[208:211], v[4:7]
	v_mfma_f32_16x16x32_bf16 v[0:3], v[152:155], v[204:207], v[0:3]
	v_mfma_f32_16x16x32_bf16 v[0:3], v[156:159], v[208:211], v[0:3]
	s_setprio 0
	s_barrier
	s_add_i32 s61, s61, 2
	s_add_u32 s22, s22, 0x80000
	s_addc_u32 s23, s23, 0
	s_add_u32 s12, s12, 0x400000
	s_addc_u32 s13, s13, 0
	s_cmp_gt_u32 s61, 13
	s_cbranch_scc0 .LBB0_952
	s_and_b64 vcc, exec, s[52:53]
	s_cbranch_vccz .LBB0_955
	s_barrier

; #define PG8_STAGE(bufoff, gbase, voff) do { _Pragma("unroll") for (int _i = 0; _i < 2; ++_i) \
;         __builtin_amdgcn_global_load_lds((const unsigned*)((const char*)(gbase) + (voff)[_i]), (LAS unsigned*)(lds + (bufoff) + ldsw + _i * 8192), 16, 0, 0); } while (0)
; #define PG8_LDA(dst, b, h) do { _Pragma("unroll") for (int m = 0; m < 4; ++m) _Pragma("unroll") for (int k = 0; k < 2; ++k) dst[m][k] = *(const LAS bf16x8*)(lds + PG8_SA(b, h) + aoff + m * 2048 + k * 1024); } while (0)
; #define PG8_LDB(dst, b, h) do { _Pragma("unroll") for (int n = 0; n < 2; ++n) _Pragma("unroll") for (int k = 0; k < 2; ++k) dst[n][k] = *(const LAS bf16x8*)(lds + PG8_SB(b, h) + boff + n * 2048 + k * 1024); } while (0)
; #define PG8_MMA(ai, bj, At, Bt) do { __builtin_amdgcn_s_setprio(1); _Pragma("unroll") for (int m = 0; m < 4; ++m) _Pragma("unroll") for (int n = 0; n < 2; ++n) _Pragma("unroll") for (int k = 0; k < 2; ++k) \
;         acc[ai][bj][m][n] = __builtin_amdgcn_mfma_f32_16x16x32_bf16(Bt[n][k], At[m][k], acc[ai][bj][m][n], 0, 0, 0); __builtin_amdgcn_s_setprio(0); } while (0)
; #define PG8_WAIT_V(n) asm volatile("s_waitcnt vmcnt(" #n ")" ::: "memory")
; #define PG8_WAIT_L(n) asm volatile("s_waitcnt lgkmcnt(" #n ")" ::: "memory")
; #define PG8_BAR __builtin_amdgcn_s_barrier()
; template <bool ALIGN_EPI, class Epi, class Sched>
; __device__ __forceinline__ void gemm_phase(LAS unsigned char* lds, const int lda, const int ldb, const int K, const Sched& S, const Epi& E, const size_t kstepA = (size_t)(BK * 2), const size_t kstepB = (size_t)(BK * 2)) {
;     ...
;             const bool last = (t == nt - 2);
;             const char* a1 = cA + (size_t)(t + 1) * kstepA;
;             const char* a2 = last ? nA : cA + (size_t)(t + 2) * kstepA; const char* b2 = last ? nB : cB + (size_t)(t + 2) * kstep;
;             const char* a3 = a2 + kstepA; const char* b3 = b2 + kstep;
;             PG8_LDB(B0, 0, 0); PG8_LDB(B1, 0, 1); PG8_SCHED; PG8_LDA(At, 0, 0); PG8_STAGE(PG8_SA(1, 1), a1 + hstepA, voffA);
;             PG8_WAIT_V(8); PG8_WAIT_L(0); PG8_BAR; PG8_MMA(0, 0, At, B0); PG8_MMA(0, 1, At, B1); PG8_BAR; PG8_SCHED;
;             PG8_LDA(At, 0, 1); PG8_STAGE(PG8_SB(0, 0), b2, voffB); PG8_STAGE(PG8_SB(0, 1), b2 + hstepB, voffB); PG8_STAGE(PG8_SA(0, 0), a2, voffA);
;             PG8_WAIT_V(8); PG8_WAIT_L(0); PG8_BAR; PG8_MMA(1, 0, At, B0); PG8_MMA(1, 1, At, B1); PG8_BAR; PG8_SCHED;
.LBB0_1044:
	ds_read_b128 v[148:151], v168
	ds_read_b128 v[172:175], v168 offset:1024
	ds_read_b128 v[176:179], v168 offset:2048
	ds_read_b128 v[180:183], v168 offset:3072
	ds_read_b128 v[186:189], v169
	ds_read_b128 v[190:193], v169 offset:1024
	ds_read_b128 v[194:197], v169 offset:2048
	ds_read_b128 v[198:201], v169 offset:3072
	s_add_u32 s48, s46, 0x1fc000
	s_addc_u32 s49, s47, 0
	s_cmp_eq_u32 s15, 28
	s_cselect_b32 s54, s22, s48
	s_cselect_b32 s55, s23, s49
	s_cselect_b32 s52, s44, s9
	s_cselect_b32 s53, s45, s13
	s_add_u32 s48, s54, 0x200000
	s_addc_u32 s49, s55, 0
	s_add_i32 m0, s29, 0xc000
	ds_read_b128 v[202:205], v170
	ds_read_b128 v[206:209], v170 offset:1024
	ds_read_b128 v[210:213], v170 offset:2048
	ds_read_b128 v[214:217], v170 offset:3072
	ds_read_b128 v[218:221], v170 offset:4096
	ds_read_b128 v[222:225], v170 offset:5120
	ds_read_b128 v[226:229], v170 offset:6144
	ds_read_b128 v[230:233], v170 offset:7168
	global_load_lds_dwordx4 v140, s[46:47]
	s_add_i32 m0, s29, 0xe000
	s_nop 0
	global_load_lds_dwordx4 v142, s[46:47]
	s_waitcnt vmcnt(8)
	s_waitcnt lgkmcnt(0)
	s_barrier
	s_setprio 1
	s_waitcnt lgkmcnt(0)
	v_mfma_f32_16x16x32_bf16 v[124:127], v[148:151], v[202:205], v[124:127]
	v_mfma_f32_16x16x32_bf16 v[124:127], v[172:175], v[206:209], v[124:127]
	v_mfma_f32_16x16x32_bf16 v[120:123], v[176:179], v[202:205], v[120:123]
	v_mfma_f32_16x16x32_bf16 v[120:123], v[180:183], v[206:209], v[120:123]
	v_mfma_f32_16x16x32_bf16 v[108:111], v[148:151], v[210:213], v[108:111]
	v_mfma_f32_16x16x32_bf16 v[108:111], v[172:175], v[214:217], v[108:111]
	v_mfma_f32_16x16x32_bf16 v[104:107], v[176:179], v[210:213], v[104:107]
	v_mfma_f32_16x16x32_bf16 v[104:107], v[180:183], v[214:217], v[104:107]
	v_mfma_f32_16x16x32_bf16 v[92:95], v[148:151], v[218:221], v[92:95]
	v_mfma_f32_16x16x32_bf16 v[92:95], v[172:175], v[222:225], v[92:95]
	v_mfma_f32_16x16x32_bf16 v[88:91], v[176:179], v[218:221], v[88:91]
	v_mfma_f32_16x16x32_bf16 v[88:91], v[180:183], v[222:225], v[88:91]
	v_mfma_f32_16x16x32_bf16 v[76:79], v[148:151], v[226:229], v[76:79]
	v_mfma_f32_16x16x32_bf16 v[76:79], v[172:175], v[230:233], v[76:79]
	v_mfma_f32_16x16x32_bf16 v[72:75], v[176:179], v[226:229], v[72:75]
	v_mfma_f32_16x16x32_bf16 v[72:75], v[180:183], v[230:233], v[72:75]
	s_setprio 0
	s_setprio 1
	v_mfma_f32_16x16x32_bf16 v[116:119], v[186:189], v[202:205], v[116:119]
	v_mfma_f32_16x16x32_bf16 v[116:119], v[190:193], v[206:209], v[116:119]
	v_mfma_f32_16x16x32_bf16 v[112:115], v[194:197], v[202:205], v[112:115]
	v_mfma_f32_16x16x32_bf16 v[112:115], v[198:201], v[206:209], v[112:115]
	v_mfma_f32_16x16x32_bf16 v[100:103], v[186:189], v[210:213], v[100:103]
	v_mfma_f32_16x16x32_bf16 v[100:103], v[190:193], v[214:217], v[100:103]
	v_mfma_f32_16x16x32_bf16 v[96:99], v[194:197], v[210:213], v[96:99]
	v_mfma_f32_16x16x32_bf16 v[96:99], v[198:201], v[214:217], v[96:99]
	v_mfma_f32_16x16x32_bf16 v[84:87], v[186:189], v[218:221], v[84:87]
	v_mfma_f32_16x16x32_bf16 v[84:87], v[190:193], v[222:225], v[84:87]
	v_mfma_f32_16x16x32_bf16 v[80:83], v[194:197], v[218:221], v[80:83]
	v_mfma_f32_16x16x32_bf16 v[80:83], v[198:201], v[222:225], v[80:83]
	v_mfma_f32_16x16x32_bf16 v[68:71], v[186:189], v[226:229], v[68:71]
	v_mfma_f32_16x16x32_bf16 v[68:71], v[190:193], v[230:233], v[68:71]
	v_mfma_f32_16x16x32_bf16 v[64:67], v[194:197], v[226:229], v[64:67]
	v_mfma_f32_16x16x32_bf16 v[64:67], v[198:201], v[230:233], v[64:67]
	s_setprio 0
	s_barrier
	s_add_i32 s61, s57, s19
	s_mov_b32 m0, s61
	ds_read_b128 v[202:205], v170 offset:16384
	ds_read_b128 v[206:209], v170 offset:17408
	ds_read_b128 v[210:213], v170 offset:18432
	ds_read_b128 v[214:217], v170 offset:19456
	ds_read_b128 v[218:221], v170 offset:20480
	ds_read_b128 v[222:225], v170 offset:21504
	ds_read_b128 v[226:229], v170 offset:22528
	ds_read_b128 v[230:233], v170 offset:23552
	global_load_lds_dwordx4 v130, s[52:53]
	s_add_i32 m0, s61, 0x2000
	s_add_u32 s62, s52, 0x4000
	s_addc_u32 s63, s53, 0
	s_add_i32 s61, s58, s19
	global_load_lds_dwordx4 v134, s[52:53]
	s_mov_b32 m0, s61
	s_nop 0
	global_load_lds_dwordx4 v130, s[62:63]
	s_add_i32 m0, s61, 0x2000
	s_nop 0
	global_load_lds_dwordx4 v134, s[62:63]
	s_mov_b32 m0, s29
	s_nop 0
	global_load_lds_dwordx4 v128, s[54:55]
	s_mov_b32 m0, s30
	s_nop 0
	global_load_lds_dwordx4 v132, s[54:55]
	s_waitcnt vmcnt(8)
	s_waitcnt lgkmcnt(0)
	s_barrier
	s_setprio 1
	s_waitcnt lgkmcnt(0)
	v_mfma_f32_16x16x32_bf16 v[60:63], v[148:151], v[202:205], v[60:63]
	v_mfma_f32_16x16x32_bf16 v[60:63], v[172:175], v[206:209], v[60:63]
	v_mfma_f32_16x16x32_bf16 v[56:59], v[176:179], v[202:205], v[56:59]
	v_mfma_f32_16x16x32_bf16 v[56:59], v[180:183], v[206:209], v[56:59]
	v_mfma_f32_16x16x32_bf16 v[44:47], v[148:151], v[210:213], v[44:47]
	v_mfma_f32_16x16x32_bf16 v[44:47], v[172:175], v[214:217], v[44:47]
	v_mfma_f32_16x16x32_bf16 v[40:43], v[176:179], v[210:213], v[40:43]
	v_mfma_f32_16x16x32_bf16 v[40:43], v[180:183], v[214:217], v[40:43]
	v_mfma_f32_16x16x32_bf16 v[28:31], v[148:151], v[218:221], v[28:31]
	v_mfma_f32_16x16x32_bf16 v[28:31], v[172:175], v[222:225], v[28:31]
	v_mfma_f32_16x16x32_bf16 v[24:27], v[176:179], v[218:221], v[24:27]
	v_mfma_f32_16x16x32_bf16 v[24:27], v[180:183], v[222:225], v[24:27]
	v_mfma_f32_16x16x32_bf16 v[12:15], v[148:151], v[226:229], v[12:15]
	v_mfma_f32_16x16x32_bf16 v[12:15], v[172:175], v[230:233], v[12:15]
	v_mfma_f32_16x16x32_bf16 v[8:11], v[176:179], v[226:229], v[8:11]
	v_mfma_f32_16x16x32_bf16 v[8:11], v[180:183], v[230:233], v[8:11]
	s_setprio 0
	s_setprio 1
	v_mfma_f32_16x16x32_bf16 v[52:55], v[186:189], v[202:205], v[52:55]
	v_mfma_f32_16x16x32_bf16 v[52:55], v[190:193], v[206:209], v[52:55]
	v_mfma_f32_16x16x32_bf16 v[48:51], v[194:197], v[202:205], v[48:51]
	v_mfma_f32_16x16x32_bf16 v[48:51], v[198:201], v[206:209], v[48:51]
	v_mfma_f32_16x16x32_bf16 v[36:39], v[186:189], v[210:213], v[36:39]
	v_mfma_f32_16x16x32_bf16 v[36:39], v[190:193], v[214:217], v[36:39]
	v_mfma_f32_16x16x32_bf16 v[32:35], v[194:197], v[210:213], v[32:35]
	v_mfma_f32_16x16x32_bf16 v[32:35], v[198:201], v[214:217], v[32:35]
	v_mfma_f32_16x16x32_bf16 v[20:23], v[186:189], v[218:221], v[20:23]
	v_mfma_f32_16x16x32_bf16 v[20:23], v[190:193], v[222:225], v[20:23]
	v_mfma_f32_16x16x32_bf16 v[16:19], v[194:197], v[218:221], v[16:19]
	v_mfma_f32_16x16x32_bf16 v[16:19], v[198:201], v[222:225], v[16:19]
	v_mfma_f32_16x16x32_bf16 v[4:7], v[186:189], v[226:229], v[4:7]
	v_mfma_f32_16x16x32_bf16 v[4:7], v[190:193], v[230:233], v[4:7]
	v_mfma_f32_16x16x32_bf16 v[0:3], v[194:197], v[226:229], v[0:3]
	v_mfma_f32_16x16x32_bf16 v[0:3], v[198:201], v[230:233], v[0:3]
	s_setprio 0
	s_barrier
; #define PG8_STAGE(bufoff, gbase, voff) do { _Pragma("unroll") for (int _i = 0; _i < 2; ++_i) \
;         __builtin_amdgcn_global_load_lds((const unsigned*)((const char*)(gbase) + (voff)[_i]), (LAS unsigned*)(lds + (bufoff) + ldsw + _i * 8192), 16, 0, 0); } while (0)
; #define PG8_LDA(dst, b, h) do { _Pragma("unroll") for (int m = 0; m < 4; ++m) _Pragma("unroll") for (int k = 0; k < 2; ++k) dst[m][k] = *(const LAS bf16x8*)(lds + PG8_SA(b, h) + aoff + m * 2048 + k * 1024); } while (0)
; #define PG8_LDB(dst, b, h) do { _Pragma("unroll") for (int n = 0; n < 2; ++n) _Pragma("unroll") for (int k = 0; k < 2; ++k) dst[n][k] = *(const LAS bf16x8*)(lds + PG8_SB(b, h) + boff + n * 2048 + k * 1024); } while (0)
; #define PG8_MMA(ai, bj, At, Bt) do { __builtin_amdgcn_s_setprio(1); _Pragma("unroll") for (int m = 0; m < 4; ++m) _Pragma("unroll") for (int n = 0; n < 2; ++n) _Pragma("unroll") for (int k = 0; k < 2; ++k) \
;         acc[ai][bj][m][n] = __builtin_amdgcn_mfma_f32_16x16x32_bf16(Bt[n][k], At[m][k], acc[ai][bj][m][n], 0, 0, 0); __builtin_amdgcn_s_setprio(0); } while (0)
; #define PG8_WAIT_V(n) asm volatile("s_waitcnt vmcnt(" #n ")" ::: "memory")
; #define PG8_WAIT_L(n) asm volatile("s_waitcnt lgkmcnt(" #n ")" ::: "memory")
; #define PG8_BAR __builtin_amdgcn_s_barrier()
; #define PG8_SCHED __builtin_amdgcn_sched_barrier(0)
; template <bool ALIGN_EPI, class Epi, class Sched>
; __device__ __forceinline__ void gemm_phase(LAS unsigned char* lds, const int lda, const int ldb, const int K, const Sched& S, const Epi& E, const size_t kstepA = (size_t)(BK * 2), const size_t kstepB = (size_t)(BK * 2)) {
;     ...
;             PG8_LDB(B0, 1, 0); PG8_LDB(B1, 1, 1); PG8_SCHED; PG8_LDA(At, 1, 0); PG8_STAGE(PG8_SA(0, 1), a2 + hstepA, voffA);
;             PG8_WAIT_V(8); PG8_WAIT_L(0); PG8_BAR; PG8_MMA(0, 0, At, B0); PG8_MMA(0, 1, At, B1); PG8_BAR; PG8_SCHED;
;             PG8_LDA(At, 1, 1); PG8_STAGE(PG8_SB(1, 0), b3, voffB); PG8_STAGE(PG8_SB(1, 1), b3 + hstepB, voffB); PG8_STAGE(PG8_SA(1, 0), a3, voffA);
;             PG8_WAIT_V(8); PG8_WAIT_L(0); PG8_BAR; PG8_MMA(1, 0, At, B0); PG8_MMA(1, 1, At, B1); PG8_BAR; PG8_SCHED;
;         }
;         if constexpr (ALIGN_EPI) { if (wr == 0) PG8_BAR; }
	s_add_i32 s61, 0, 0x18000
	v_add_u32_e32 v136, s61, v152
	s_add_i32 s62, 0, 0x1c000
	ds_read_b128 v[148:151], v136
	ds_read_b128 v[172:175], v136 offset:1024
	ds_read_b128 v[176:179], v136 offset:2048
	ds_read_b128 v[180:183], v136 offset:3072
	v_add_u32_e32 v136, s62, v152
	ds_read_b128 v[186:189], v136
	ds_read_b128 v[190:193], v136 offset:1024
	ds_read_b128 v[194:197], v136 offset:2048
	ds_read_b128 v[198:201], v136 offset:3072
	s_add_u32 s54, s54, 0x4000
	s_addc_u32 s55, s55, 0
	s_mov_b32 m0, s31
	ds_read_b128 v[202:205], v170 offset:32768
	ds_read_b128 v[206:209], v170 offset:33792
	ds_read_b128 v[210:213], v170 offset:34816
	ds_read_b128 v[214:217], v170 offset:35840
	ds_read_b128 v[218:221], v170 offset:36864
	ds_read_b128 v[222:225], v170 offset:37888
	ds_read_b128 v[226:229], v170 offset:38912
	ds_read_b128 v[230:233], v170 offset:39936
	global_load_lds_dwordx4 v128, s[54:55]
	s_mov_b32 m0, s33
	s_nop 0
	global_load_lds_dwordx4 v132, s[54:55]
	s_waitcnt vmcnt(8)
	s_waitcnt lgkmcnt(0)
	s_barrier
	s_setprio 1
	s_waitcnt lgkmcnt(0)
	v_mfma_f32_16x16x32_bf16 v[124:127], v[148:151], v[202:205], v[124:127]
	v_mfma_f32_16x16x32_bf16 v[124:127], v[172:175], v[206:209], v[124:127]
	v_mfma_f32_16x16x32_bf16 v[120:123], v[176:179], v[202:205], v[120:123]
	v_mfma_f32_16x16x32_bf16 v[120:123], v[180:183], v[206:209], v[120:123]
	v_mfma_f32_16x16x32_bf16 v[108:111], v[148:151], v[210:213], v[108:111]
	v_mfma_f32_16x16x32_bf16 v[108:111], v[172:175], v[214:217], v[108:111]
	v_mfma_f32_16x16x32_bf16 v[104:107], v[176:179], v[210:213], v[104:107]
	v_mfma_f32_16x16x32_bf16 v[104:107], v[180:183], v[214:217], v[104:107]
	v_mfma_f32_16x16x32_bf16 v[92:95], v[148:151], v[218:221], v[92:95]
	v_mfma_f32_16x16x32_bf16 v[92:95], v[172:175], v[222:225], v[92:95]
	v_mfma_f32_16x16x32_bf16 v[88:91], v[176:179], v[218:221], v[88:91]
	v_mfma_f32_16x16x32_bf16 v[88:91], v[180:183], v[222:225], v[88:91]
	v_mfma_f32_16x16x32_bf16 v[76:79], v[148:151], v[226:229], v[76:79]
	v_mfma_f32_16x16x32_bf16 v[76:79], v[172:175], v[230:233], v[76:79]
	v_mfma_f32_16x16x32_bf16 v[72:75], v[176:179], v[226:229], v[72:75]
	v_mfma_f32_16x16x32_bf16 v[72:75], v[180:183], v[230:233], v[72:75]
	s_setprio 0
	s_setprio 1
	v_mfma_f32_16x16x32_bf16 v[116:119], v[186:189], v[202:205], v[116:119]
	v_mfma_f32_16x16x32_bf16 v[116:119], v[190:193], v[206:209], v[116:119]
	v_mfma_f32_16x16x32_bf16 v[112:115], v[194:197], v[202:205], v[112:115]
	v_mfma_f32_16x16x32_bf16 v[112:115], v[198:201], v[206:209], v[112:115]
	v_mfma_f32_16x16x32_bf16 v[100:103], v[186:189], v[210:213], v[100:103]
	v_mfma_f32_16x16x32_bf16 v[100:103], v[190:193], v[214:217], v[100:103]
	v_mfma_f32_16x16x32_bf16 v[96:99], v[194:197], v[210:213], v[96:99]
	v_mfma_f32_16x16x32_bf16 v[96:99], v[198:201], v[214:217], v[96:99]
	v_mfma_f32_16x16x32_bf16 v[84:87], v[186:189], v[218:221], v[84:87]
	v_mfma_f32_16x16x32_bf16 v[84:87], v[190:193], v[222:225], v[84:87]
	v_mfma_f32_16x16x32_bf16 v[80:83], v[194:197], v[218:221], v[80:83]
	v_mfma_f32_16x16x32_bf16 v[80:83], v[198:201], v[222:225], v[80:83]
	v_mfma_f32_16x16x32_bf16 v[68:71], v[186:189], v[226:229], v[68:71]
	v_mfma_f32_16x16x32_bf16 v[68:71], v[190:193], v[230:233], v[68:71]
	v_mfma_f32_16x16x32_bf16 v[64:67], v[194:197], v[226:229], v[64:67]
	v_mfma_f32_16x16x32_bf16 v[64:67], v[198:201], v[230:233], v[64:67]
	s_setprio 0
	s_barrier
	s_add_u32 s54, s52, 0x160000
	s_addc_u32 s55, s53, 0
	s_add_i32 s61, s61, s19
	s_mov_b32 m0, s61
	ds_read_b128 v[202:205], v170 offset:49152
	ds_read_b128 v[206:209], v170 offset:50176
	ds_read_b128 v[210:213], v170 offset:51200
	ds_read_b128 v[214:217], v170 offset:52224
	ds_read_b128 v[218:221], v170 offset:53248
	ds_read_b128 v[222:225], v170 offset:54272
	ds_read_b128 v[226:229], v170 offset:55296
	ds_read_b128 v[230:233], v170 offset:56320
	global_load_lds_dwordx4 v130, s[54:55]
	s_add_i32 m0, s61, 0x2000
	s_add_u32 s52, s52, 0x164000
	global_load_lds_dwordx4 v134, s[54:55]
	s_addc_u32 s53, s53, 0
	s_add_i32 s54, s62, s19
	s_mov_b32 m0, s54
	s_nop 0
	global_load_lds_dwordx4 v130, s[52:53]
	s_add_i32 m0, s54, 0x2000
	s_nop 0
	global_load_lds_dwordx4 v134, s[52:53]
	s_mov_b32 m0, s50
	s_nop 0
	global_load_lds_dwordx4 v128, s[48:49]
	s_mov_b32 m0, s51
	s_nop 0
	global_load_lds_dwordx4 v132, s[48:49]
	s_waitcnt vmcnt(8)
	s_waitcnt lgkmcnt(0)
	s_barrier
	s_setprio 1
	s_waitcnt lgkmcnt(0)
	v_mfma_f32_16x16x32_bf16 v[60:63], v[148:151], v[202:205], v[60:63]
	v_mfma_f32_16x16x32_bf16 v[60:63], v[172:175], v[206:209], v[60:63]
	v_mfma_f32_16x16x32_bf16 v[56:59], v[176:179], v[202:205], v[56:59]
	v_mfma_f32_16x16x32_bf16 v[56:59], v[180:183], v[206:209], v[56:59]
	v_mfma_f32_16x16x32_bf16 v[44:47], v[148:151], v[210:213], v[44:47]
	v_mfma_f32_16x16x32_bf16 v[44:47], v[172:175], v[214:217], v[44:47]
	v_mfma_f32_16x16x32_bf16 v[40:43], v[176:179], v[210:213], v[40:43]
	v_mfma_f32_16x16x32_bf16 v[40:43], v[180:183], v[214:217], v[40:43]
	v_mfma_f32_16x16x32_bf16 v[28:31], v[148:151], v[218:221], v[28:31]
	v_mfma_f32_16x16x32_bf16 v[28:31], v[172:175], v[222:225], v[28:31]
	v_mfma_f32_16x16x32_bf16 v[24:27], v[176:179], v[218:221], v[24:27]
	v_mfma_f32_16x16x32_bf16 v[24:27], v[180:183], v[222:225], v[24:27]
	v_mfma_f32_16x16x32_bf16 v[12:15], v[148:151], v[226:229], v[12:15]
	v_mfma_f32_16x16x32_bf16 v[12:15], v[172:175], v[230:233], v[12:15]
	v_mfma_f32_16x16x32_bf16 v[8:11], v[176:179], v[226:229], v[8:11]
	v_mfma_f32_16x16x32_bf16 v[8:11], v[180:183], v[230:233], v[8:11]
	s_setprio 0
	s_setprio 1
	v_mfma_f32_16x16x32_bf16 v[52:55], v[186:189], v[202:205], v[52:55]
	v_mfma_f32_16x16x32_bf16 v[52:55], v[190:193], v[206:209], v[52:55]
	v_mfma_f32_16x16x32_bf16 v[48:51], v[194:197], v[202:205], v[48:51]
	v_mfma_f32_16x16x32_bf16 v[48:51], v[198:201], v[206:209], v[48:51]
	v_mfma_f32_16x16x32_bf16 v[36:39], v[186:189], v[210:213], v[36:39]
	v_mfma_f32_16x16x32_bf16 v[36:39], v[190:193], v[214:217], v[36:39]
	v_mfma_f32_16x16x32_bf16 v[32:35], v[194:197], v[210:213], v[32:35]
	v_mfma_f32_16x16x32_bf16 v[32:35], v[198:201], v[214:217], v[32:35]
	v_mfma_f32_16x16x32_bf16 v[20:23], v[186:189], v[218:221], v[20:23]
	v_mfma_f32_16x16x32_bf16 v[20:23], v[190:193], v[222:225], v[20:23]
	v_mfma_f32_16x16x32_bf16 v[16:19], v[194:197], v[218:221], v[16:19]
	v_mfma_f32_16x16x32_bf16 v[16:19], v[198:201], v[222:225], v[16:19]
	v_mfma_f32_16x16x32_bf16 v[4:7], v[186:189], v[226:229], v[4:7]
	v_mfma_f32_16x16x32_bf16 v[4:7], v[190:193], v[230:233], v[4:7]
	v_mfma_f32_16x16x32_bf16 v[0:3], v[194:197], v[226:229], v[0:3]
	v_mfma_f32_16x16x32_bf16 v[0:3], v[198:201], v[230:233], v[0:3]
	s_setprio 0
	s_barrier
	s_add_i32 s15, s15, 2
	s_add_u32 s9, s9, 0x2c0000
	s_addc_u32 s13, s13, 0
	s_add_u32 s46, s46, 0x400000
	s_addc_u32 s47, s47, 0
	s_cmp_gt_u32 s15, 29
	s_cbranch_scc0 .LBB0_1044
	s_and_b64 vcc, exec, s[10:11]
	s_cbranch_vccz .LBB0_1047
	s_barrier

; #define PG8_STAGE(bufoff, gbase, voff) do { _Pragma("unroll") for (int _i = 0; _i < 2; ++_i) \
;         __builtin_amdgcn_global_load_lds((const unsigned*)((const char*)(gbase) + (voff)[_i]), (LAS unsigned*)(lds + (bufoff) + ldsw + _i * 8192), 16, 0, 0); } while (0)
; #define PG8_LDA(dst, b, h) do { _Pragma("unroll") for (int m = 0; m < 4; ++m) _Pragma("unroll") for (int k = 0; k < 2; ++k) dst[m][k] = *(const LAS bf16x8*)(lds + PG8_SA(b, h) + aoff + m * 2048 + k * 1024); } while (0)
; #define PG8_LDB(dst, b, h) do { _Pragma("unroll") for (int n = 0; n < 2; ++n) _Pragma("unroll") for (int k = 0; k < 2; ++k) dst[n][k] = *(const LAS bf16x8*)(lds + PG8_SB(b, h) + boff + n * 2048 + k * 1024); } while (0)
; #define PG8_MMA(ai, bj, At, Bt) do { __builtin_amdgcn_s_setprio(1); _Pragma("unroll") for (int m = 0; m < 4; ++m) _Pragma("unroll") for (int n = 0; n < 2; ++n) _Pragma("unroll") for (int k = 0; k < 2; ++k) \
;         acc[ai][bj][m][n] = __builtin_amdgcn_mfma_f32_16x16x32_bf16(Bt[n][k], At[m][k], acc[ai][bj][m][n], 0, 0, 0); __builtin_amdgcn_s_setprio(0); } while (0)
; #define PG8_WAIT_V(n) asm volatile("s_waitcnt vmcnt(" #n ")" ::: "memory")
; #define PG8_WAIT_L(n) asm volatile("s_waitcnt lgkmcnt(" #n ")" ::: "memory")
; #define PG8_BAR __builtin_amdgcn_s_barrier()
; template <bool ALIGN_EPI, class Epi, class Sched>
; __device__ __forceinline__ void gemm_phase(LAS unsigned char* lds, const int lda, const int ldb, const int K, const Sched& S, const Epi& E, const size_t kstepA = (size_t)(BK * 2), const size_t kstepB = (size_t)(BK * 2)) {
;     ...
;             const bool last = (t == nt - 2);
;             const char* a1 = cA + (size_t)(t + 1) * kstepA;
;             const char* a2 = last ? nA : cA + (size_t)(t + 2) * kstepA; const char* b2 = last ? nB : cB + (size_t)(t + 2) * kstep;
;             const char* a3 = a2 + kstepA; const char* b3 = b2 + kstep;
;             PG8_LDB(B0, 0, 0); PG8_LDB(B1, 0, 1); PG8_SCHED; PG8_LDA(At, 0, 0); PG8_STAGE(PG8_SA(1, 1), a1 + hstepA, voffA);
;             PG8_WAIT_V(8); PG8_WAIT_L(0); PG8_BAR; PG8_MMA(0, 0, At, B0); PG8_MMA(0, 1, At, B1); PG8_BAR; PG8_SCHED;
;             PG8_LDA(At, 0, 1); PG8_STAGE(PG8_SB(0, 0), b2, voffB); PG8_STAGE(PG8_SB(0, 1), b2 + hstepB, voffB); PG8_STAGE(PG8_SA(0, 0), a2, voffA);
;             PG8_WAIT_V(8); PG8_WAIT_L(0); PG8_BAR; PG8_MMA(1, 0, At, B0); PG8_MMA(1, 1, At, B1); PG8_BAR; PG8_SCHED;
.LBB0_1154:
	ds_read_b128 v[80:83], v219
	ds_read_b128 v[84:87], v219 offset:1024
	ds_read_b128 v[104:107], v219 offset:2048
	ds_read_b128 v[108:111], v219 offset:3072
	ds_read_b128 v[144:147], v220
	ds_read_b128 v[148:151], v220 offset:1024
	ds_read_b128 v[152:155], v220 offset:2048
	ds_read_b128 v[156:159], v220 offset:3072
	s_add_u32 s12, s10, 0x1fc000
	s_addc_u32 s13, s11, 0
	s_cmpk_eq_i32 s67, 0x54
	s_cselect_b32 s16, s0, s12
	s_cselect_b32 s17, s1, s13
	s_cselect_b32 s14, s8, s57
	s_cselect_b32 s15, s9, s59
	s_add_u32 s12, s16, 0x200000
	s_addc_u32 s13, s17, 0
	s_add_i32 m0, s19, 0xc000
	ds_read_b128 v[160:163], v221
	ds_read_b128 v[164:167], v221 offset:1024
	ds_read_b128 v[188:191], v221 offset:2048
	ds_read_b128 v[192:195], v221 offset:3072
	ds_read_b128 v[196:199], v221 offset:4096
	ds_read_b128 v[200:203], v221 offset:5120
	ds_read_b128 v[204:207], v221 offset:6144
	ds_read_b128 v[208:211], v221 offset:7168
	global_load_lds_dwordx4 v178, s[10:11]
	s_add_i32 m0, s19, 0xe000
	s_nop 0
	global_load_lds_dwordx4 v180, s[10:11]
	s_waitcnt vmcnt(8)
	s_waitcnt lgkmcnt(0)
	s_barrier
	s_setprio 1
	s_waitcnt lgkmcnt(0)
	v_mfma_f32_16x16x32_bf16 v[140:143], v[80:83], v[160:163], v[140:143]
	v_mfma_f32_16x16x32_bf16 v[140:143], v[84:87], v[164:167], v[140:143]
	v_mfma_f32_16x16x32_bf16 v[136:139], v[104:107], v[160:163], v[136:139]
	v_mfma_f32_16x16x32_bf16 v[136:139], v[108:111], v[164:167], v[136:139]
	v_mfma_f32_16x16x32_bf16 v[124:127], v[80:83], v[188:191], v[124:127]
	v_mfma_f32_16x16x32_bf16 v[124:127], v[84:87], v[192:195], v[124:127]
	v_mfma_f32_16x16x32_bf16 v[120:123], v[104:107], v[188:191], v[120:123]
	v_mfma_f32_16x16x32_bf16 v[120:123], v[108:111], v[192:195], v[120:123]
	v_mfma_f32_16x16x32_bf16 v[100:103], v[80:83], v[196:199], v[100:103]
	v_mfma_f32_16x16x32_bf16 v[100:103], v[84:87], v[200:203], v[100:103]
	v_mfma_f32_16x16x32_bf16 v[96:99], v[104:107], v[196:199], v[96:99]
	v_mfma_f32_16x16x32_bf16 v[96:99], v[108:111], v[200:203], v[96:99]
	v_mfma_f32_16x16x32_bf16 v[76:79], v[80:83], v[204:207], v[76:79]
	v_mfma_f32_16x16x32_bf16 v[76:79], v[84:87], v[208:211], v[76:79]
	v_mfma_f32_16x16x32_bf16 v[72:75], v[104:107], v[204:207], v[72:75]
	v_mfma_f32_16x16x32_bf16 v[72:75], v[108:111], v[208:211], v[72:75]
	s_setprio 0
	s_setprio 1
	v_mfma_f32_16x16x32_bf16 v[132:135], v[144:147], v[160:163], v[132:135]
	v_mfma_f32_16x16x32_bf16 v[132:135], v[148:151], v[164:167], v[132:135]
	v_mfma_f32_16x16x32_bf16 v[128:131], v[152:155], v[160:163], v[128:131]
	v_mfma_f32_16x16x32_bf16 v[128:131], v[156:159], v[164:167], v[128:131]
	v_mfma_f32_16x16x32_bf16 v[116:119], v[144:147], v[188:191], v[116:119]
	v_mfma_f32_16x16x32_bf16 v[116:119], v[148:151], v[192:195], v[116:119]
	v_mfma_f32_16x16x32_bf16 v[112:115], v[152:155], v[188:191], v[112:115]
	v_mfma_f32_16x16x32_bf16 v[112:115], v[156:159], v[192:195], v[112:115]
	v_mfma_f32_16x16x32_bf16 v[92:95], v[144:147], v[196:199], v[92:95]
	v_mfma_f32_16x16x32_bf16 v[92:95], v[148:151], v[200:203], v[92:95]
	v_mfma_f32_16x16x32_bf16 v[88:91], v[152:155], v[196:199], v[88:91]
	v_mfma_f32_16x16x32_bf16 v[88:91], v[156:159], v[200:203], v[88:91]
	v_mfma_f32_16x16x32_bf16 v[68:71], v[144:147], v[204:207], v[68:71]
	v_mfma_f32_16x16x32_bf16 v[68:71], v[148:151], v[208:211], v[68:71]
	v_mfma_f32_16x16x32_bf16 v[64:67], v[152:155], v[204:207], v[64:67]
	v_mfma_f32_16x16x32_bf16 v[64:67], v[156:159], v[208:211], v[64:67]
	s_setprio 0
	s_barrier
	s_add_i32 s68, s51, s18
	s_mov_b32 m0, s68
	ds_read_b128 v[160:163], v221 offset:16384
	ds_read_b128 v[164:167], v221 offset:17408
	ds_read_b128 v[188:191], v221 offset:18432
	ds_read_b128 v[192:195], v221 offset:19456
	ds_read_b128 v[196:199], v221 offset:20480
	ds_read_b128 v[200:203], v221 offset:21504
	ds_read_b128 v[204:207], v221 offset:22528
	ds_read_b128 v[208:211], v221 offset:23552
	global_load_lds_dwordx4 v170, s[14:15]
	s_add_i32 m0, s68, 0x2000
	s_add_u32 s68, s14, 0x4000
	s_addc_u32 s69, s15, 0
	s_add_i32 s70, s64, s18
	global_load_lds_dwordx4 v174, s[14:15]
	s_mov_b32 m0, s70
	s_nop 0
	global_load_lds_dwordx4 v170, s[68:69]
	s_add_i32 m0, s70, 0x2000
	s_nop 0
	global_load_lds_dwordx4 v174, s[68:69]
	s_mov_b32 m0, s19
	s_nop 0
	global_load_lds_dwordx4 v168, s[16:17]
	s_mov_b32 m0, s29
	s_nop 0
	global_load_lds_dwordx4 v172, s[16:17]
	s_waitcnt vmcnt(8)
	s_waitcnt lgkmcnt(0)
	s_barrier
	s_setprio 1
	s_waitcnt lgkmcnt(0)
	v_mfma_f32_16x16x32_bf16 v[60:63], v[80:83], v[160:163], v[60:63]
	v_mfma_f32_16x16x32_bf16 v[60:63], v[84:87], v[164:167], v[60:63]
	v_mfma_f32_16x16x32_bf16 v[56:59], v[104:107], v[160:163], v[56:59]
	v_mfma_f32_16x16x32_bf16 v[56:59], v[108:111], v[164:167], v[56:59]
	v_mfma_f32_16x16x32_bf16 v[44:47], v[80:83], v[188:191], v[44:47]
	v_mfma_f32_16x16x32_bf16 v[44:47], v[84:87], v[192:195], v[44:47]
	v_mfma_f32_16x16x32_bf16 v[40:43], v[104:107], v[188:191], v[40:43]
	v_mfma_f32_16x16x32_bf16 v[40:43], v[108:111], v[192:195], v[40:43]
	v_mfma_f32_16x16x32_bf16 v[28:31], v[80:83], v[196:199], v[28:31]
	v_mfma_f32_16x16x32_bf16 v[28:31], v[84:87], v[200:203], v[28:31]
	v_mfma_f32_16x16x32_bf16 v[24:27], v[104:107], v[196:199], v[24:27]
	v_mfma_f32_16x16x32_bf16 v[24:27], v[108:111], v[200:203], v[24:27]
	v_mfma_f32_16x16x32_bf16 v[12:15], v[80:83], v[204:207], v[12:15]
	v_mfma_f32_16x16x32_bf16 v[12:15], v[84:87], v[208:211], v[12:15]
	v_mfma_f32_16x16x32_bf16 v[8:11], v[104:107], v[204:207], v[8:11]
	v_mfma_f32_16x16x32_bf16 v[8:11], v[108:111], v[208:211], v[8:11]
	s_setprio 0
	s_setprio 1
	v_mfma_f32_16x16x32_bf16 v[52:55], v[144:147], v[160:163], v[52:55]
	v_mfma_f32_16x16x32_bf16 v[52:55], v[148:151], v[164:167], v[52:55]
	v_mfma_f32_16x16x32_bf16 v[48:51], v[152:155], v[160:163], v[48:51]
	v_mfma_f32_16x16x32_bf16 v[48:51], v[156:159], v[164:167], v[48:51]
	v_mfma_f32_16x16x32_bf16 v[36:39], v[144:147], v[188:191], v[36:39]
	v_mfma_f32_16x16x32_bf16 v[36:39], v[148:151], v[192:195], v[36:39]
	v_mfma_f32_16x16x32_bf16 v[32:35], v[152:155], v[188:191], v[32:35]
	v_mfma_f32_16x16x32_bf16 v[32:35], v[156:159], v[192:195], v[32:35]
	v_mfma_f32_16x16x32_bf16 v[20:23], v[144:147], v[196:199], v[20:23]
	v_mfma_f32_16x16x32_bf16 v[20:23], v[148:151], v[200:203], v[20:23]
	v_mfma_f32_16x16x32_bf16 v[16:19], v[152:155], v[196:199], v[16:19]
	v_mfma_f32_16x16x32_bf16 v[16:19], v[156:159], v[200:203], v[16:19]
	v_mfma_f32_16x16x32_bf16 v[4:7], v[144:147], v[204:207], v[4:7]
	v_mfma_f32_16x16x32_bf16 v[4:7], v[148:151], v[208:211], v[4:7]
	v_mfma_f32_16x16x32_bf16 v[0:3], v[152:155], v[204:207], v[0:3]
	v_mfma_f32_16x16x32_bf16 v[0:3], v[156:159], v[208:211], v[0:3]
	s_setprio 0
	s_barrier
; #define PG8_STAGE(bufoff, gbase, voff) do { _Pragma("unroll") for (int _i = 0; _i < 2; ++_i) \
;         __builtin_amdgcn_global_load_lds((const unsigned*)((const char*)(gbase) + (voff)[_i]), (LAS unsigned*)(lds + (bufoff) + ldsw + _i * 8192), 16, 0, 0); } while (0)
; #define PG8_LDA(dst, b, h) do { _Pragma("unroll") for (int m = 0; m < 4; ++m) _Pragma("unroll") for (int k = 0; k < 2; ++k) dst[m][k] = *(const LAS bf16x8*)(lds + PG8_SA(b, h) + aoff + m * 2048 + k * 1024); } while (0)
; #define PG8_LDB(dst, b, h) do { _Pragma("unroll") for (int n = 0; n < 2; ++n) _Pragma("unroll") for (int k = 0; k < 2; ++k) dst[n][k] = *(const LAS bf16x8*)(lds + PG8_SB(b, h) + boff + n * 2048 + k * 1024); } while (0)
; #define PG8_MMA(ai, bj, At, Bt) do { __builtin_amdgcn_s_setprio(1); _Pragma("unroll") for (int m = 0; m < 4; ++m) _Pragma("unroll") for (int n = 0; n < 2; ++n) _Pragma("unroll") for (int k = 0; k < 2; ++k) \
;         acc[ai][bj][m][n] = __builtin_amdgcn_mfma_f32_16x16x32_bf16(Bt[n][k], At[m][k], acc[ai][bj][m][n], 0, 0, 0); __builtin_amdgcn_s_setprio(0); } while (0)
; #define PG8_WAIT_V(n) asm volatile("s_waitcnt vmcnt(" #n ")" ::: "memory")
; #define PG8_WAIT_L(n) asm volatile("s_waitcnt lgkmcnt(" #n ")" ::: "memory")
; #define PG8_BAR __builtin_amdgcn_s_barrier()
; #define PG8_SCHED __builtin_amdgcn_sched_barrier(0)
; template <bool ALIGN_EPI, class Epi, class Sched>
; __device__ __forceinline__ void gemm_phase(LAS unsigned char* lds, const int lda, const int ldb, const int K, const Sched& S, const Epi& E, const size_t kstepA = (size_t)(BK * 2), const size_t kstepB = (size_t)(BK * 2)) {
;     ...
;             PG8_LDB(B0, 1, 0); PG8_LDB(B1, 1, 1); PG8_SCHED; PG8_LDA(At, 1, 0); PG8_STAGE(PG8_SA(0, 1), a2 + hstepA, voffA);
;             PG8_WAIT_V(8); PG8_WAIT_L(0); PG8_BAR; PG8_MMA(0, 0, At, B0); PG8_MMA(0, 1, At, B1); PG8_BAR; PG8_SCHED;
;             PG8_LDA(At, 1, 1); PG8_STAGE(PG8_SB(1, 0), b3, voffB); PG8_STAGE(PG8_SB(1, 1), b3 + hstepB, voffB); PG8_STAGE(PG8_SA(1, 0), a3, voffA);
;             PG8_WAIT_V(8); PG8_WAIT_L(0); PG8_BAR; PG8_MMA(1, 0, At, B0); PG8_MMA(1, 1, At, B1); PG8_BAR; PG8_SCHED;
;         }
;         if constexpr (ALIGN_EPI) { if (wr == 0) PG8_BAR; }
	s_add_i32 s68, 0, 0x18000
	s_add_i32 s69, 0, 0x1c000
	v_add_u32_e32 v108, s68, v218
	v_add_u32_e32 v156, s69, v218
	ds_read_b128 v[80:83], v108
	ds_read_b128 v[84:87], v108 offset:1024
	ds_read_b128 v[104:107], v108 offset:2048
	ds_read_b128 v[108:111], v108 offset:3072
	ds_read_b128 v[144:147], v156
	ds_read_b128 v[148:151], v156 offset:1024
	ds_read_b128 v[152:155], v156 offset:2048
	ds_read_b128 v[156:159], v156 offset:3072
	s_add_u32 s16, s16, 0x4000
	s_addc_u32 s17, s17, 0
	s_mov_b32 m0, s30
	ds_read_b128 v[160:163], v221 offset:32768
	ds_read_b128 v[164:167], v221 offset:33792
	ds_read_b128 v[188:191], v221 offset:34816
	ds_read_b128 v[192:195], v221 offset:35840
	ds_read_b128 v[196:199], v221 offset:36864
	ds_read_b128 v[200:203], v221 offset:37888
	ds_read_b128 v[204:207], v221 offset:38912
	ds_read_b128 v[208:211], v221 offset:39936
	global_load_lds_dwordx4 v168, s[16:17]
	s_mov_b32 m0, s31
	s_nop 0
	global_load_lds_dwordx4 v172, s[16:17]
	s_waitcnt vmcnt(8)
	s_waitcnt lgkmcnt(0)
	s_barrier
	s_setprio 1
	s_waitcnt lgkmcnt(0)
	v_mfma_f32_16x16x32_bf16 v[140:143], v[80:83], v[160:163], v[140:143]
	v_mfma_f32_16x16x32_bf16 v[140:143], v[84:87], v[164:167], v[140:143]
	v_mfma_f32_16x16x32_bf16 v[136:139], v[104:107], v[160:163], v[136:139]
	v_mfma_f32_16x16x32_bf16 v[136:139], v[108:111], v[164:167], v[136:139]
	v_mfma_f32_16x16x32_bf16 v[124:127], v[80:83], v[188:191], v[124:127]
	v_mfma_f32_16x16x32_bf16 v[124:127], v[84:87], v[192:195], v[124:127]
	v_mfma_f32_16x16x32_bf16 v[120:123], v[104:107], v[188:191], v[120:123]
	v_mfma_f32_16x16x32_bf16 v[120:123], v[108:111], v[192:195], v[120:123]
	v_mfma_f32_16x16x32_bf16 v[100:103], v[80:83], v[196:199], v[100:103]
	v_mfma_f32_16x16x32_bf16 v[100:103], v[84:87], v[200:203], v[100:103]
	v_mfma_f32_16x16x32_bf16 v[96:99], v[104:107], v[196:199], v[96:99]
	v_mfma_f32_16x16x32_bf16 v[96:99], v[108:111], v[200:203], v[96:99]
	v_mfma_f32_16x16x32_bf16 v[76:79], v[80:83], v[204:207], v[76:79]
	v_mfma_f32_16x16x32_bf16 v[76:79], v[84:87], v[208:211], v[76:79]
	v_mfma_f32_16x16x32_bf16 v[72:75], v[104:107], v[204:207], v[72:75]
	v_mfma_f32_16x16x32_bf16 v[72:75], v[108:111], v[208:211], v[72:75]
	s_setprio 0
	s_setprio 1
	v_mfma_f32_16x16x32_bf16 v[132:135], v[144:147], v[160:163], v[132:135]
	v_mfma_f32_16x16x32_bf16 v[132:135], v[148:151], v[164:167], v[132:135]
	v_mfma_f32_16x16x32_bf16 v[128:131], v[152:155], v[160:163], v[128:131]
	v_mfma_f32_16x16x32_bf16 v[128:131], v[156:159], v[164:167], v[128:131]
	v_mfma_f32_16x16x32_bf16 v[116:119], v[144:147], v[188:191], v[116:119]
	v_mfma_f32_16x16x32_bf16 v[116:119], v[148:151], v[192:195], v[116:119]
	v_mfma_f32_16x16x32_bf16 v[112:115], v[152:155], v[188:191], v[112:115]
	v_mfma_f32_16x16x32_bf16 v[112:115], v[156:159], v[192:195], v[112:115]
	v_mfma_f32_16x16x32_bf16 v[92:95], v[144:147], v[196:199], v[92:95]
	v_mfma_f32_16x16x32_bf16 v[92:95], v[148:151], v[200:203], v[92:95]
	v_mfma_f32_16x16x32_bf16 v[88:91], v[152:155], v[196:199], v[88:91]
	v_mfma_f32_16x16x32_bf16 v[88:91], v[156:159], v[200:203], v[88:91]
	v_mfma_f32_16x16x32_bf16 v[68:71], v[144:147], v[204:207], v[68:71]
	v_mfma_f32_16x16x32_bf16 v[68:71], v[148:151], v[208:211], v[68:71]
	v_mfma_f32_16x16x32_bf16 v[64:67], v[152:155], v[204:207], v[64:67]
	v_mfma_f32_16x16x32_bf16 v[64:67], v[156:159], v[208:211], v[64:67]
	s_setprio 0
	s_barrier
	s_add_u32 s16, s14, 0x40000
	s_addc_u32 s17, s15, 0
	s_add_i32 s68, s68, s18
	s_mov_b32 m0, s68
	ds_read_b128 v[160:163], v221 offset:49152
	ds_read_b128 v[164:167], v221 offset:50176
	ds_read_b128 v[188:191], v221 offset:51200
	ds_read_b128 v[192:195], v221 offset:52224
	ds_read_b128 v[196:199], v221 offset:53248
	ds_read_b128 v[200:203], v221 offset:54272
	ds_read_b128 v[204:207], v221 offset:55296
	ds_read_b128 v[208:211], v221 offset:56320
	global_load_lds_dwordx4 v170, s[16:17]
	s_add_i32 m0, s68, 0x2000
	s_add_u32 s14, s14, 0x44000
	global_load_lds_dwordx4 v174, s[16:17]
	s_addc_u32 s15, s15, 0
	s_add_i32 s16, s69, s18
	s_mov_b32 m0, s16
	s_nop 0
	global_load_lds_dwordx4 v170, s[14:15]
	s_add_i32 m0, s16, 0x2000
	s_nop 0
	global_load_lds_dwordx4 v174, s[14:15]
	s_mov_b32 m0, s43
	s_nop 0
	global_load_lds_dwordx4 v168, s[12:13]
	s_mov_b32 m0, s50
	s_nop 0
	global_load_lds_dwordx4 v172, s[12:13]
	s_waitcnt vmcnt(8)
	s_waitcnt lgkmcnt(0)
	s_barrier
	s_setprio 1
	s_waitcnt lgkmcnt(0)
	v_mfma_f32_16x16x32_bf16 v[60:63], v[80:83], v[160:163], v[60:63]
	v_mfma_f32_16x16x32_bf16 v[60:63], v[84:87], v[164:167], v[60:63]
	v_mfma_f32_16x16x32_bf16 v[56:59], v[104:107], v[160:163], v[56:59]
	v_mfma_f32_16x16x32_bf16 v[56:59], v[108:111], v[164:167], v[56:59]
	v_mfma_f32_16x16x32_bf16 v[44:47], v[80:83], v[188:191], v[44:47]
	v_mfma_f32_16x16x32_bf16 v[44:47], v[84:87], v[192:195], v[44:47]
	v_mfma_f32_16x16x32_bf16 v[40:43], v[104:107], v[188:191], v[40:43]
	v_mfma_f32_16x16x32_bf16 v[40:43], v[108:111], v[192:195], v[40:43]
	v_mfma_f32_16x16x32_bf16 v[28:31], v[80:83], v[196:199], v[28:31]
	v_mfma_f32_16x16x32_bf16 v[28:31], v[84:87], v[200:203], v[28:31]
	v_mfma_f32_16x16x32_bf16 v[24:27], v[104:107], v[196:199], v[24:27]
	v_mfma_f32_16x16x32_bf16 v[24:27], v[108:111], v[200:203], v[24:27]
	v_mfma_f32_16x16x32_bf16 v[12:15], v[80:83], v[204:207], v[12:15]
	v_mfma_f32_16x16x32_bf16 v[12:15], v[84:87], v[208:211], v[12:15]
	v_mfma_f32_16x16x32_bf16 v[8:11], v[104:107], v[204:207], v[8:11]
	v_mfma_f32_16x16x32_bf16 v[8:11], v[108:111], v[208:211], v[8:11]
	s_setprio 0
	s_setprio 1
	v_mfma_f32_16x16x32_bf16 v[52:55], v[144:147], v[160:163], v[52:55]
	v_mfma_f32_16x16x32_bf16 v[52:55], v[148:151], v[164:167], v[52:55]
	v_mfma_f32_16x16x32_bf16 v[48:51], v[152:155], v[160:163], v[48:51]
	v_mfma_f32_16x16x32_bf16 v[48:51], v[156:159], v[164:167], v[48:51]
	v_mfma_f32_16x16x32_bf16 v[36:39], v[144:147], v[188:191], v[36:39]
	v_mfma_f32_16x16x32_bf16 v[36:39], v[148:151], v[192:195], v[36:39]
	v_mfma_f32_16x16x32_bf16 v[32:35], v[152:155], v[188:191], v[32:35]
	v_mfma_f32_16x16x32_bf16 v[32:35], v[156:159], v[192:195], v[32:35]
	v_mfma_f32_16x16x32_bf16 v[20:23], v[144:147], v[196:199], v[20:23]
	v_mfma_f32_16x16x32_bf16 v[20:23], v[148:151], v[200:203], v[20:23]
	v_mfma_f32_16x16x32_bf16 v[16:19], v[152:155], v[196:199], v[16:19]
	v_mfma_f32_16x16x32_bf16 v[16:19], v[156:159], v[200:203], v[16:19]
	v_mfma_f32_16x16x32_bf16 v[4:7], v[144:147], v[204:207], v[4:7]
	v_mfma_f32_16x16x32_bf16 v[4:7], v[148:151], v[208:211], v[4:7]
	v_mfma_f32_16x16x32_bf16 v[0:3], v[152:155], v[204:207], v[0:3]
	v_mfma_f32_16x16x32_bf16 v[0:3], v[156:159], v[208:211], v[0:3]
	s_setprio 0
	s_barrier
	s_add_i32 s67, s67, 2
	s_add_u32 s57, s57, 0x80000
	s_addc_u32 s59, s59, 0
	s_add_u32 s10, s10, 0x400000
	s_addc_u32 s11, s11, 0
	s_cmpk_gt_u32 s67, 0x55
	s_cbranch_scc0 .LBB0_1154
	s_and_b64 vcc, exec, s[46:47]
	s_cbranch_vccz .LBB0_1157
	s_barrier
